# LRU item x-tile staged to LDS by LDS-DMA one chunk ahead (removes serialised global loads); attention K/V fragment LDS reads issued through a ring of free register quads
# speedup vs baseline: 1.0485x; 1.0185x over previous
; #define LAS __attribute__((address_space(3)))
; __device__ __forceinline__ f32x16 mfma32(bf16x8 a, bf16x8 b, f32x16 c) { return __builtin_amdgcn_mfma_f32_32x32x16_bf16(a, b, c, 0, 0, 0); }
; __device__ __forceinline__ void attn_unit(LAS unsigned char* lds, const Params& P, int l, int b, int h, int qi, float lam, float post_scale, float kn2) {
;     ...
;         if (kt * 64 <= q0 + 31) {
;             const float base2 = slope2 * (float)(kt * 64 + 8 * hh - (q0 + r)) - mused;
;             f32x16 s[2];
; #pragma unroll
;             for (int kb = 0; kb < 2; ++kb) {
; #pragma unroll
;                 for (int i = 0; i < 16; ++i) s[kb][i] = __builtin_fmaf(slope2, (float)(32 * kb + (i & 7) + 16 * (i >> 3)), base2);
; #pragma unroll
;                 for (int kk = 0; kk < 4; ++kk) { const bf16x8 kf = *(const LAS bf16x8*)(kbuf + koff + kb * 32 * AT_KPITCH + kk * 32); s[kb] = mfma32(kf, qf[kk], s[kb]); }
;             }
;             if (kt * 64 + 63 > q0) {
;                 const int thr = q0 + r - kt * 64 - 8 * hh;
; #pragma unroll
;                 for (int kb = 0; kb < 2; ++kb)
; #pragma unroll
;                     for (int i = 0; i < 16; ++i) { const int keyl = 32 * kb + (i & 7) + 16 * (i >> 3); s[kb][i] = (keyl > thr) ? -INFINITY : s[kb][i]; }
;             }
.LBB0_218:
	v_add_u32_e32 v1, s73, v227
	v_cvt_f32_i32_e32 v1, v1
	s_bitcmp1_b32 s74, 0
	s_cselect_b32 s20, 0x4800, 0
	v_mov_b32_e32 v173, v172
	v_fma_f32 v12, v172, v1, -v228
	v_add_u32_e32 v1, s20, v169
	ds_read_b128 v[4:7], v1
	ds_read_b128 v[8:11], v1 offset:32
	ds_read_b128 v[232:235], v1 offset:64
	ds_read_b128 v[236:239], v1 offset:96
	v_fma_f32 v80, 0, v172, v12
	v_add_f32_e32 v81, v172, v12
	v_pk_fma_f32 v[82:83], v[180:181], s[28:29], v[12:13] op_sel_hi:[1,1,0]
	v_pk_fma_f32 v[84:85], v[180:181], s[30:31], v[12:13] op_sel_hi:[1,1,0]
	v_pk_fma_f32 v[86:87], v[180:181], s[34:35], v[12:13] op_sel_hi:[1,1,0]
	v_pk_fma_f32 v[88:89], v[180:181], s[36:37], v[12:13] op_sel_hi:[1,1,0]
	v_pk_fma_f32 v[90:91], v[180:181], s[38:39], v[12:13] op_sel_hi:[1,1,0]
	v_pk_fma_f32 v[92:93], v[180:181], s[40:41], v[12:13] op_sel_hi:[1,1,0]
	v_pk_fma_f32 v[94:95], v[180:181], s[42:43], v[12:13] op_sel_hi:[1,1,0]
	v_pk_fma_f32 v[110:111], v[172:173], s[44:45], v[12:13] op_sel_hi:[1,1,0]
	v_pk_fma_f32 v[108:109], v[172:173], s[46:47], v[12:13] op_sel_hi:[1,1,0]
	s_waitcnt lgkmcnt(3)
	v_mfma_f32_32x32x16_bf16 v[80:95], v[4:7], v[112:115], v[80:95]
	ds_read_b128 v[4:7], v1 offset:4608
	v_fma_f32 v106, v172, s48, v12
	v_fma_f32 v107, v173, s49, v12
	v_fma_f32 v104, v172, s50, v12
	v_fma_f32 v105, v173, s51, v12
	v_pk_fma_f32 v[102:103], v[172:173], s[52:53], v[12:13] op_sel_hi:[1,1,0]
	v_pk_fma_f32 v[100:101], v[172:173], s[54:55], v[12:13] op_sel_hi:[1,1,0]
	v_pk_fma_f32 v[98:99], v[172:173], s[56:57], v[12:13] op_sel_hi:[1,1,0]
	v_pk_fma_f32 v[96:97], v[182:183], s[58:59], v[12:13] op_sel_hi:[1,1,0]
	s_waitcnt lgkmcnt(3)
	v_mfma_f32_32x32x16_bf16 v[80:95], v[8:11], v[116:119], v[80:95]
	ds_read_b128 v[8:11], v1 offset:4640
	s_addk_i32 s17, 0x7f
	s_cmp_le_i32 s17, s70
	s_waitcnt lgkmcnt(3)
	v_mfma_f32_32x32x16_bf16 v[80:95], v[232:235], v[120:123], v[80:95]
	ds_read_b128 v[232:235], v1 offset:4672
	s_waitcnt lgkmcnt(3)
	v_mfma_f32_32x32x16_bf16 v[80:95], v[236:239], v[124:127], v[80:95]
	ds_read_b128 v[236:239], v1 offset:4704
	s_waitcnt lgkmcnt(3)
	v_mfma_f32_32x32x16_bf16 v[96:111], v[4:7], v[112:115], v[96:111]
	s_waitcnt lgkmcnt(2)
	v_mfma_f32_32x32x16_bf16 v[96:111], v[8:11], v[116:119], v[96:111]
	s_waitcnt lgkmcnt(1)
	v_mfma_f32_32x32x16_bf16 v[96:111], v[232:235], v[120:123], v[96:111]
	s_waitcnt lgkmcnt(0)
	v_mfma_f32_32x32x16_bf16 v[96:111], v[236:239], v[124:127], v[96:111]
	s_cbranch_scc1 .LBB0_220
	v_cmp_lt_i32_e32 vcc, -1, v226
	s_nop 1
	v_cndmask_b32_e32 v80, v222, v80, vcc
	v_cmp_lt_i32_e32 vcc, 0, v226
	s_nop 1
	v_cndmask_b32_e32 v81, v222, v81, vcc
	v_cmp_lt_i32_e32 vcc, 1, v226
	s_nop 1
	v_cndmask_b32_e32 v82, v222, v82, vcc
	v_cmp_lt_i32_e32 vcc, 2, v226
	s_nop 1
	v_cndmask_b32_e32 v83, v222, v83, vcc
	v_cmp_lt_i32_e32 vcc, 3, v226
	s_nop 1
	v_cndmask_b32_e32 v84, v222, v84, vcc
	v_cmp_lt_i32_e32 vcc, 4, v226
	s_nop 1
	v_cndmask_b32_e32 v85, v222, v85, vcc
	v_cmp_lt_i32_e32 vcc, 5, v226
	s_nop 1
	v_cndmask_b32_e32 v86, v222, v86, vcc
	v_cmp_lt_i32_e32 vcc, 6, v226
	s_nop 1
	v_cndmask_b32_e32 v87, v222, v87, vcc
	v_cmp_lt_i32_e32 vcc, 15, v226
	s_nop 1
	v_cndmask_b32_e32 v88, v222, v88, vcc
	v_cmp_lt_i32_e32 vcc, 16, v226
	s_nop 1
	v_cndmask_b32_e32 v89, v222, v89, vcc
	v_cmp_lt_i32_e32 vcc, 17, v226
	s_nop 1
	v_cndmask_b32_e32 v90, v222, v90, vcc
	v_cmp_lt_i32_e32 vcc, 18, v226
	s_nop 1
	v_cndmask_b32_e32 v91, v222, v91, vcc
	v_cmp_lt_i32_e32 vcc, 19, v226
	s_nop 1
	v_cndmask_b32_e32 v92, v222, v92, vcc
	v_cmp_lt_i32_e32 vcc, 20, v226
	s_nop 1
	v_cndmask_b32_e32 v93, v222, v93, vcc
	v_cmp_lt_i32_e32 vcc, 21, v226
	s_nop 1
	v_cndmask_b32_e32 v94, v222, v94, vcc
	v_cmp_lt_i32_e32 vcc, 22, v226
	s_nop 1
	v_cndmask_b32_e32 v95, v222, v95, vcc
	v_cmp_lt_i32_e32 vcc, 31, v226
	s_nop 1
	v_cndmask_b32_e32 v96, v222, v96, vcc
	v_cmp_lt_i32_e32 vcc, 32, v226
	s_nop 1
	v_cndmask_b32_e32 v97, v222, v97, vcc
	v_cmp_lt_i32_e32 vcc, 33, v226
	s_nop 1
	v_cndmask_b32_e32 v98, v222, v98, vcc
	v_cmp_lt_i32_e32 vcc, 34, v226
	s_nop 1
	v_cndmask_b32_e32 v99, v222, v99, vcc
	v_cmp_lt_i32_e32 vcc, 35, v226
	s_nop 1
	v_cndmask_b32_e32 v100, v222, v100, vcc
	v_cmp_lt_i32_e32 vcc, 36, v226
	s_nop 1
	v_cndmask_b32_e32 v101, v222, v101, vcc
	v_cmp_lt_i32_e32 vcc, 37, v226
	s_nop 1
	v_cndmask_b32_e32 v102, v222, v102, vcc
	v_cmp_lt_i32_e32 vcc, 38, v226
	s_nop 1
	v_cndmask_b32_e32 v103, v222, v103, vcc
	v_cmp_lt_i32_e32 vcc, 47, v226
	s_nop 1
	v_cndmask_b32_e32 v104, v222, v104, vcc
	v_cmp_lt_i32_e32 vcc, 48, v226
	s_nop 1
	v_cndmask_b32_e32 v105, v222, v105, vcc
	v_cmp_lt_i32_e32 vcc, 49, v226
	s_nop 1
	v_cndmask_b32_e32 v106, v222, v106, vcc
	v_cmp_lt_i32_e32 vcc, 50, v226
	s_nop 1
	v_cndmask_b32_e32 v107, v222, v107, vcc
	v_cmp_lt_i32_e32 vcc, 51, v226
	s_nop 1
	v_cndmask_b32_e32 v108, v222, v108, vcc
	v_cmp_lt_i32_e32 vcc, 52, v226
	s_nop 1
	v_cndmask_b32_e32 v109, v222, v109, vcc
	v_cmp_lt_i32_e32 vcc, 53, v226
	s_nop 1
	v_cndmask_b32_e32 v110, v222, v110, vcc
	v_cmp_lt_i32_e32 vcc, 54, v226
	s_nop 1
	v_cndmask_b32_e32 v111, v222, v111, vcc

; #define LAS __attribute__((address_space(3)))
; __device__ __forceinline__ unsigned cvt_pk_bf16(float lo, float hi) { const f32x2 v = {lo, hi}; return __builtin_bit_cast(unsigned, __builtin_convertvector(v, bf16x2v)); }
; __device__ __forceinline__ float fexp2(float x) { return __builtin_amdgcn_exp2f(x); }
; #define AT_PV(vbase) do { _Pragma("unroll") for (int e = 0; e < 4; ++e) _Pragma("unroll") for (int kb = 0; kb < 2; ++kb) _Pragma("unroll") for (int st = 0; st < 2; ++st) { \
;         const bf16x8 vf = *(const LAS bf16x8*)((vbase) + voff + e * 32 * AT_KPITCH + (32 * kb + 16 * st) * 2); o[e] = mfma32(vf, pf[kb][st], o[e]); } } while (0)
; __device__ __forceinline__ void attn_unit(LAS unsigned char* lds, const Params& P, int l, int b, int h, int qi, float lam, float post_scale, float kn2) {
;     ...
;             float psum = 0.f;
; #pragma unroll
;             for (int kb = 0; kb < 2; ++kb)
; #pragma unroll
;                 for (int i = 0; i < 16; ++i) { const float p = fexp2(s[kb][i]); psum += p; s[kb][i] = p; }
;             lsum += psum;
; #pragma unroll
;             for (int kb = 0; kb < 2; ++kb)
; #pragma unroll
;                 for (int st = 0; st < 2; ++st) { u32x4 t; t.x = cvt_pk_bf16(s[kb][8 * st + 0], s[kb][8 * st + 1]); t.y = cvt_pk_bf16(s[kb][8 * st + 2], s[kb][8 * st + 3]);
;                     t.z = cvt_pk_bf16(s[kb][8 * st + 4], s[kb][8 * st + 5]); t.w = cvt_pk_bf16(s[kb][8 * st + 6], s[kb][8 * st + 7]); pf[kb][st] = __builtin_bit_cast(bf16x8, t); }
;             if (map == 0) { LAS unsigned char* vcur = lds + AT_VRING + (kt % 3) * AT_VSLOT; AT_PV(vcur); }
.LBB0_227:
	v_exp_f32_e32 v173, v80
	v_exp_f32_e32 v229, v81
	v_exp_f32_e32 v230, v82
	v_exp_f32_e32 v231, v83
	v_exp_f32_e32 v232, v84
	v_exp_f32_e32 v233, v85
	v_exp_f32_e32 v234, v86
	v_exp_f32_e32 v235, v87
	v_exp_f32_e32 v236, v88
	v_exp_f32_e32 v237, v89
	v_exp_f32_e32 v238, v90
	v_exp_f32_e32 v239, v91
	v_exp_f32_e32 v240, v92
	v_exp_f32_e32 v241, v93
	v_exp_f32_e32 v242, v94
	v_exp_f32_e32 v243, v95
	v_exp_f32_e32 v1, v96
	v_exp_f32_e32 v3, v97
	v_exp_f32_e32 v4, v98
	v_exp_f32_e32 v5, v99
	v_exp_f32_e32 v6, v100
	v_exp_f32_e32 v7, v101
	v_exp_f32_e32 v8, v102
	v_exp_f32_e32 v9, v103
	v_exp_f32_e32 v10, v104
	v_exp_f32_e32 v11, v105
	v_exp_f32_e32 v12, v106
	v_exp_f32_e32 v13, v107
	v_exp_f32_e32 v14, v108
	v_exp_f32_e32 v15, v109
	v_exp_f32_e32 v96, v110
	v_exp_f32_e32 v97, v111
	v_cvt_pk_bf16_f32 v80, v173, v229
	v_cvt_pk_bf16_f32 v81, v230, v231
	v_cvt_pk_bf16_f32 v82, v232, v233
	v_cvt_pk_bf16_f32 v83, v234, v235
	v_cvt_pk_bf16_f32 v88, v236, v237
	v_cvt_pk_bf16_f32 v89, v238, v239
	v_cvt_pk_bf16_f32 v90, v240, v241
	v_cvt_pk_bf16_f32 v91, v242, v243
	v_cvt_pk_bf16_f32 v84, v1, v3
	v_cvt_pk_bf16_f32 v85, v4, v5
	v_cvt_pk_bf16_f32 v86, v6, v7
	v_cvt_pk_bf16_f32 v87, v8, v9
	v_cvt_pk_bf16_f32 v92, v10, v11
	v_cvt_pk_bf16_f32 v93, v12, v13
	v_cvt_pk_bf16_f32 v94, v14, v15
	v_cvt_pk_bf16_f32 v95, v96, v97
	s_andn2_b64 vcc, exec, s[60:61]
	s_mov_b64 s[66:67], -1
	s_cbranch_vccnz .LBB0_229
	s_mul_hi_i32 s17, s74, 0x55555556
	s_lshr_b32 s20, s17, 31
	s_add_i32 s17, s17, s20
	s_mul_i32 s17, s17, 3
	s_sub_i32 s17, s74, s17
	s_mulk_i32 s17, 0x4800
	v_add_u32_e32 v102, s17, v184
	ds_read_b128 v[98:101], v102 offset:36864
	ds_read_b128 v[104:107], v102 offset:41472
	ds_read_b128 v[108:111], v102 offset:36896
	s_mov_b64 s[66:67], 0
	s_waitcnt lgkmcnt(2)
	v_mfma_f32_32x32x16_bf16 v[64:79], v[98:101], v[80:83], v[64:79]
	ds_read_b128 v[98:101], v102 offset:36928
	s_waitcnt lgkmcnt(2)
	v_mfma_f32_32x32x16_bf16 v[48:63], v[104:107], v[80:83], v[48:63]
	ds_read_b128 v[104:107], v102 offset:36960
	s_waitcnt lgkmcnt(2)
	v_mfma_f32_32x32x16_bf16 v[64:79], v[108:111], v[88:91], v[64:79]
	ds_read_b128 v[108:111], v102 offset:41504
	s_waitcnt lgkmcnt(2)
	v_mfma_f32_32x32x16_bf16 v[64:79], v[98:101], v[84:87], v[64:79]
	ds_read_b128 v[98:101], v102 offset:41536
	s_waitcnt lgkmcnt(2)
	v_mfma_f32_32x32x16_bf16 v[64:79], v[104:107], v[92:95], v[64:79]
	ds_read_b128 v[104:107], v102 offset:41568
	s_waitcnt lgkmcnt(2)
	v_mfma_f32_32x32x16_bf16 v[48:63], v[108:111], v[88:91], v[48:63]
	ds_read_b128 v[108:111], v102 offset:46080
	s_waitcnt lgkmcnt(2)
	v_mfma_f32_32x32x16_bf16 v[48:63], v[98:101], v[84:87], v[48:63]
	ds_read_b128 v[98:101], v102 offset:46112
	s_waitcnt lgkmcnt(2)
	v_mfma_f32_32x32x16_bf16 v[48:63], v[104:107], v[92:95], v[48:63]
	ds_read_b128 v[104:107], v102 offset:46144
	s_waitcnt lgkmcnt(2)
	v_mfma_f32_32x32x16_bf16 v[32:47], v[108:111], v[80:83], v[32:47]
	ds_read_b128 v[108:111], v102 offset:46176
	s_waitcnt lgkmcnt(2)
	v_mfma_f32_32x32x16_bf16 v[32:47], v[98:101], v[88:91], v[32:47]
	ds_read_b128 v[98:101], v102 offset:50688
	s_waitcnt lgkmcnt(2)
	v_mfma_f32_32x32x16_bf16 v[32:47], v[104:107], v[84:87], v[32:47]
	ds_read_b128 v[104:107], v102 offset:50720
	s_waitcnt lgkmcnt(2)
	v_mfma_f32_32x32x16_bf16 v[32:47], v[108:111], v[92:95], v[32:47]
	ds_read_b128 v[108:111], v102 offset:50752
	s_waitcnt lgkmcnt(2)
	v_mfma_f32_32x32x16_bf16 v[16:31], v[98:101], v[80:83], v[16:31]
	ds_read_b128 v[98:101], v102 offset:50784
	s_waitcnt lgkmcnt(2)
	v_mfma_f32_32x32x16_bf16 v[16:31], v[104:107], v[88:91], v[16:31]
	s_waitcnt lgkmcnt(1)
	v_mfma_f32_32x32x16_bf16 v[16:31], v[108:111], v[84:87], v[16:31]
	s_waitcnt lgkmcnt(0)
	v_mfma_f32_32x32x16_bf16 v[16:31], v[98:101], v[92:95], v[16:31]

; #define LAS __attribute__((address_space(3)))
; #define AT_LOAD(kt) do { kreg[0] = *(const u32x4*)(kg0 + (size_t)(kt) * 64 * DM); kreg[1] = *(const u32x4*)(kg0 + (size_t)(kt) * 64 * DM + 64); \
;                          vreg[0] = *(const u32x4*)(vg0 + (kt) * 64); vreg[1] = *(const u32x4*)(vg0 + (size_t)64 * T + (kt) * 64); } while (0)
; #define AT_PV(vbase) do { _Pragma("unroll") for (int e = 0; e < 4; ++e) _Pragma("unroll") for (int kb = 0; kb < 2; ++kb) _Pragma("unroll") for (int st = 0; st < 2; ++st) { \
;         const bf16x8 vf = *(const LAS bf16x8*)((vbase) + voff + e * 32 * AT_KPITCH + (32 * kb + 16 * st) * 2); o[e] = mfma32(vf, pf[kb][st], o[e]); } } while (0)
; __device__ __forceinline__ void attn_unit(LAS unsigned char* lds, const Params& P, int l, int b, int h, int qi, float lam, float post_scale, float kn2) {
;     ...
;         if (kt > ktmin) AT_LOAD(kt - 1);
;         LAS unsigned char* kbuf = lds + (kt & 1) * AT_KSLOT;
;         if (pend) { LAS unsigned char* vprev = lds + AT_VRING + ((kt + 1) % 3) * AT_VSLOT; AT_PV(vprev); pend = false; }
.LBB0_231:
	s_add_i32 s17, s16, 2
	s_mul_hi_i32 s20, s17, 0x55555556
	s_lshr_b32 s66, s20, 31
	s_add_i32 s20, s20, s66
	s_mul_i32 s20, s20, 3
	s_sub_i32 s17, s17, s20
	s_mulk_i32 s17, 0x4800
	v_add_u32_e32 v1, s17, v184
	ds_read_b128 v[4:7], v1 offset:36864
	ds_read_b128 v[8:11], v1 offset:41472
	ds_read_b128 v[96:99], v1 offset:36896
	ds_read_b128 v[100:103], v1 offset:36928
	s_waitcnt lgkmcnt(3)
	v_mfma_f32_32x32x16_bf16 v[64:79], v[4:7], v[80:83], v[64:79]
	ds_read_b128 v[4:7], v1 offset:36960
	s_waitcnt lgkmcnt(3)
	v_mfma_f32_32x32x16_bf16 v[48:63], v[8:11], v[80:83], v[48:63]
	ds_read_b128 v[8:11], v1 offset:41504
	s_waitcnt lgkmcnt(3)
	v_mfma_f32_32x32x16_bf16 v[64:79], v[96:99], v[88:91], v[64:79]
	ds_read_b128 v[96:99], v1 offset:41536
	s_waitcnt lgkmcnt(3)
	v_mfma_f32_32x32x16_bf16 v[64:79], v[100:103], v[84:87], v[64:79]
	ds_read_b128 v[100:103], v1 offset:41568
	s_waitcnt lgkmcnt(3)
	v_mfma_f32_32x32x16_bf16 v[64:79], v[4:7], v[92:95], v[64:79]
	ds_read_b128 v[4:7], v1 offset:46080
	s_waitcnt lgkmcnt(3)
	v_mfma_f32_32x32x16_bf16 v[48:63], v[8:11], v[88:91], v[48:63]
	ds_read_b128 v[8:11], v1 offset:46112
	s_waitcnt lgkmcnt(3)
	v_mfma_f32_32x32x16_bf16 v[48:63], v[96:99], v[84:87], v[48:63]
	ds_read_b128 v[96:99], v1 offset:46144
	s_waitcnt lgkmcnt(3)
	v_mfma_f32_32x32x16_bf16 v[48:63], v[100:103], v[92:95], v[48:63]
	ds_read_b128 v[100:103], v1 offset:46176
	s_waitcnt lgkmcnt(3)
	v_mfma_f32_32x32x16_bf16 v[32:47], v[4:7], v[80:83], v[32:47]
	ds_read_b128 v[4:7], v1 offset:50688
	s_waitcnt lgkmcnt(3)
	v_mfma_f32_32x32x16_bf16 v[32:47], v[8:11], v[88:91], v[32:47]
	ds_read_b128 v[8:11], v1 offset:50720
	s_waitcnt lgkmcnt(3)
	v_mfma_f32_32x32x16_bf16 v[32:47], v[96:99], v[84:87], v[32:47]
	ds_read_b128 v[96:99], v1 offset:50752
	s_waitcnt lgkmcnt(3)
	v_mfma_f32_32x32x16_bf16 v[32:47], v[100:103], v[92:95], v[32:47]
	ds_read_b128 v[100:103], v1 offset:50784
	s_waitcnt lgkmcnt(3)
	v_mfma_f32_32x32x16_bf16 v[16:31], v[4:7], v[80:83], v[16:31]
	s_waitcnt lgkmcnt(2)
	v_mfma_f32_32x32x16_bf16 v[16:31], v[8:11], v[88:91], v[16:31]
	s_waitcnt lgkmcnt(1)
	v_mfma_f32_32x32x16_bf16 v[16:31], v[96:99], v[84:87], v[16:31]
	s_waitcnt lgkmcnt(0)
	v_mfma_f32_32x32x16_bf16 v[16:31], v[100:103], v[92:95], v[16:31]
	s_add_i32 s17, s33, s73
	s_add_i32 s20, s17, 64
	s_cmp_gt_i32 s20, s72
	s_cbranch_scc0 .LBB0_218

; #define LAS __attribute__((address_space(3)))
; __device__ __forceinline__ void lru_item(LAS unsigned char* lds, const Params& P, int l, int b, int g) {
;     const int tid = threadIdx.x, lane = tid & 63, w = __builtin_amdgcn_readfirstlane(tid >> 6);
;     const int r = lane & 31, hh = lane >> 5;
;     const int c = tid & 127, sc = tid >> 7, c0 = g * 128;
;     const bf16_t* XR = (const bf16_t*)(P.ws + WS_R4); bf16_t* GR = (bf16_t*)(P.ws + WS_R5);
;     bf16x8 bfr[8];
;     { const bf16_t* wg = (const bf16_t*)(P.ws + WS_WG) + ((size_t)(l * 8 + g) * 256 + 32 * w + r) * 128 + hh * 8;
; #pragma unroll
;       for (int kk = 0; kk < 8; ++kk) bfr[kk] = *(const bf16x8*)(wg + kk * 16); }
;     const int ch_g = l * DM + c0 + c;
;     const float cw0 = P.conv_w[(l * 4 + 0) * DM + c0 + c], cw1 = P.conv_w[(l * 4 + 1) * DM + c0 + c], cw2 = P.conv_w[(l * 4 + 2) * DM + c0 + c], cw3 = P.conv_w[(l * 4 + 3) * DM + c0 + c];
;     const float cb = P.conv_b[ch_g], ba = P.gate_a_b[ch_g], bx = P.gate_x_b[ch_g];
;     const float sp = log1pf(expf(-P.lru_lambda[ch_g]));
;     const float nsp8 = -8.0f * sp * LOG2E;
;     LAS bf16_t* Abf = (LAS bf16_t*)lds;
;     LAS float* G = (LAS float*)(lds + 17408);
;     LAS f32x2* comp = (LAS f32x2*)(lds + 83968);
;     LAS float* carry = (LAS float*)(lds + 88064);
;     if (tid < 128) carry[tid] = 0.f;
;     const size_t rowb = (size_t)b * SEQ;
;     for (int ch = 0; ch < 64; ++ch) {
;         const int sbase = ch * 64 + 16 * sc;
;         float xrv[19]; unsigned short grv[16];
; #pragma unroll
;         for (int i = 0; i < 19; ++i) { const int s = sbase - 3 + i; xrv[i] = (s >= 0) ? bf2f(XR[(rowb + (s >= 0 ? s : 0)) * DM + c0 + c]) : 0.f; }
.LBB0_243:
	s_and_b64 vcc, exec, s[16:17]
	s_cbranch_vccz .LBB0_202
	v_readfirstlane_b32 s0, v160
	s_ashr_i32 s19, s18, 31
	s_lshr_b32 s0, s0, 1
	s_lshl_b64 s[16:17], s[18:19], 8
	s_and_b32 s1, s0, 0x7fffffe0
	s_add_u32 s0, s16, s1
	s_addc_u32 s16, s17, 0
	s_load_dwordx16 s[60:75], s[96:97], 0x0
	v_mov_b32_e32 v3, s16
	v_or_b32_e32 v2, s0, v146
	v_lshlrev_b64 v[2:3], 8, v[2:3]
	v_lshl_add_u64 v[2:3], v[154:155], 0, v[2:3]
	s_lshl_b32 s16, s18, 7
	global_load_dwordx4 v[18:21], v[2:3], off
	global_load_dwordx4 v[22:25], v[2:3], off offset:32
	global_load_dwordx4 v[26:29], v[2:3], off offset:64
	global_load_dwordx4 v[30:33], v[2:3], off offset:96
	global_load_dwordx4 v[34:37], v[2:3], off offset:128
	global_load_dwordx4 v[38:41], v[2:3], off offset:160
	global_load_dwordx4 v[42:45], v[2:3], off offset:192
	global_load_dwordx4 v[46:49], v[2:3], off offset:224
	v_or_b32_e32 v2, s16, v186
	v_ashrrev_i32_e32 v3, 31, v2
	s_waitcnt lgkmcnt(0)
	s_mov_b64 s[60:61], s[64:65]
	v_lshlrev_b64 v[2:3], 2, v[2:3]
	s_mov_b64 s[62:63], s[66:67]
	s_mov_b64 s[64:65], s[68:69]
	v_add_u32_e32 v6, s16, v187
	v_add_u32_e32 v8, s16, v188
	v_add_u32_e32 v10, s16, v189
	s_mov_b64 s[66:67], s[70:71]
	v_lshl_add_u64 v[4:5], s[64:65], 0, v[2:3]
	v_ashrrev_i32_e32 v7, 31, v6
	v_ashrrev_i32_e32 v9, 31, v8
	v_ashrrev_i32_e32 v11, 31, v10
	s_mov_b64 s[70:71], s[74:75]
	v_lshl_add_u64 v[6:7], v[6:7], 2, s[64:65]
	v_lshl_add_u64 v[8:9], v[8:9], 2, s[64:65]
	v_lshl_add_u64 v[10:11], v[10:11], 2, s[64:65]
	global_load_dword v50, v[4:5], off
	global_load_dword v51, v[6:7], off
	global_load_dword v53, v[8:9], off
	global_load_dword v52, v[10:11], off
	v_lshl_add_u64 v[4:5], s[66:67], 0, v[2:3]
	global_load_dword v106, v[4:5], off
	v_lshl_add_u64 v[4:5], s[70:71], 0, v[2:3]
	s_load_dwordx16 s[60:75], s[96:97], 0x40
	global_load_dword v107, v[4:5], off
	s_waitcnt lgkmcnt(0)
	v_lshl_add_u64 v[4:5], s[62:63], 0, v[2:3]
	v_lshl_add_u64 v[2:3], s[64:65], 0, v[2:3]
	global_load_dword v108, v[4:5], off
	global_load_dword v1, v[2:3], off
	s_and_saveexec_b64 s[18:19], s[6:7]
	ds_write_b32 v190, v0
	s_or_b64 exec, exec, s[18:19]
	s_waitcnt vmcnt(0)
	v_mul_f32_e32 v2, 0xbfb8aa3b, v1
	v_rndne_f32_e32 v3, v2
	s_mov_b32 s0, 0xbfb8aa3b
	v_sub_f32_e32 v4, v2, v3
	v_fma_f32 v2, v1, s0, -v2
	v_fmac_f32_e32 v2, 0xb2a5705f, v1
	v_add_f32_e32 v2, v4, v2
	v_cvt_i32_f32_e32 v3, v3
	v_exp_f32_e32 v2, v2
	s_mov_b32 s0, 0x42ce8ed0
	v_cmp_nlt_f32_e32 vcc, s0, v1
	s_mov_b32 s0, 0xc2b17218
	v_ldexp_f32 v2, v2, v3
	v_cndmask_b32_e32 v2, 0, v2, vcc
	v_cmp_ngt_f32_e32 vcc, s0, v1
	s_mov_b32 s17, 0x3f2aaaab
	v_lshl_add_u32 v110, s1, 2, v194
	v_cndmask_b32_e32 v1, v223, v2, vcc
	v_add_f32_e32 v4, 1.0, v1
	v_add_f32_e32 v2, -1.0, v4
	v_sub_f32_e32 v3, v2, v4
	v_add_f32_e32 v3, 1.0, v3
	v_sub_f32_e32 v2, v1, v2
	v_add_f32_e32 v5, v2, v3
	v_frexp_mant_f32_e32 v6, v4
	v_cvt_f64_f32_e32 v[2:3], v4
	v_frexp_exp_i32_f64_e32 v2, v[2:3]
	v_cmp_gt_f32_e32 vcc, s17, v6
	s_mov_b32 s17, 0x3f317218
	s_mov_b32 s0, 0
	v_subbrev_co_u32_e32 v2, vcc, 0, v2, vcc
	v_sub_u32_e32 v3, 0, v2
	v_ldexp_f32 v4, v4, v3
	v_ldexp_f32 v3, v5, v3
	v_add_f32_e32 v5, -1.0, v4
	v_add_f32_e32 v8, 1.0, v4
	v_add_f32_e32 v6, 1.0, v5
	v_add_f32_e32 v9, -1.0, v8
	v_sub_f32_e32 v6, v4, v6
	v_sub_f32_e32 v4, v4, v9
	v_add_f32_e32 v6, v3, v6
	v_add_f32_e32 v3, v3, v4
	v_add_f32_e32 v4, v8, v3
	v_rcp_f32_e32 v9, v4
	v_add_f32_e32 v7, v5, v6
	v_sub_f32_e32 v5, v5, v7
	v_add_f32_e32 v5, v6, v5
	v_sub_f32_e32 v6, v8, v4
	v_add_f32_e32 v3, v3, v6
	v_mul_f32_e32 v6, v7, v9
	v_mul_f32_e32 v8, v4, v6
	v_fma_f32 v10, v6, v4, -v8
	v_fmac_f32_e32 v10, v6, v3
	v_add_f32_e32 v11, v8, v10
	v_sub_f32_e32 v12, v7, v11
	v_sub_f32_e32 v7, v7, v12
	v_sub_f32_e32 v8, v11, v8
	v_sub_f32_e32 v7, v7, v11
	v_add_f32_e32 v5, v5, v7
	v_sub_f32_e32 v7, v8, v10
	v_add_f32_e32 v5, v7, v5
	v_add_f32_e32 v7, v12, v5
	v_mul_f32_e32 v8, v9, v7
	v_mul_f32_e32 v10, v4, v8
	v_fma_f32 v4, v8, v4, -v10
	v_fmac_f32_e32 v4, v8, v3
	v_sub_f32_e32 v3, v12, v7
	v_add_f32_e32 v3, v5, v3
	v_add_f32_e32 v5, v10, v4
	v_sub_f32_e32 v11, v7, v5
	v_sub_f32_e32 v7, v7, v11
	v_sub_f32_e32 v10, v5, v10
	v_sub_f32_e32 v5, v7, v5
	v_add_f32_e32 v3, v3, v5
	v_sub_f32_e32 v4, v10, v4
	v_cvt_f32_i32_e32 v2, v2
	v_add_f32_e32 v3, v4, v3
	v_add_f32_e32 v4, v6, v8
	v_add_f32_e32 v3, v11, v3
	v_sub_f32_e32 v5, v4, v6
	v_mul_f32_e32 v3, v9, v3
	v_sub_f32_e32 v5, v8, v5
	v_add_f32_e32 v3, v5, v3
	v_mul_f32_e32 v8, 0x3f317218, v2
	v_add_f32_e32 v5, v4, v3
	v_fma_f32 v9, v2, s17, -v8
	v_mul_f32_e32 v6, v5, v5
	v_fmac_f32_e32 v9, 0xb102e308, v2
	v_sub_f32_e32 v2, v5, v4
	v_fmamk_f32 v7, v6, 0x3e9b6dac, v217
	v_sub_f32_e32 v2, v3, v2
	v_add_f32_e32 v3, v8, v9
	v_fmaak_f32 v7, v6, v7, 0x3f2aaada
	v_sub_f32_e32 v4, v3, v8
	v_ldexp_f32 v8, v5, 1
	v_mul_f32_e32 v5, v5, v6
	v_mul_f32_e32 v5, v5, v7
	v_add_f32_e32 v6, v8, v5
	v_sub_f32_e32 v7, v6, v8
	v_ldexp_f32 v2, v2, 1
	v_sub_f32_e32 v5, v5, v7
	v_add_f32_e32 v2, v2, v5
	v_add_f32_e32 v5, v6, v2
	v_sub_f32_e32 v6, v5, v6
	v_sub_f32_e32 v2, v2, v6
	v_add_f32_e32 v6, v3, v5
	v_sub_f32_e32 v7, v6, v3
	v_sub_f32_e32 v8, v6, v7
	v_sub_f32_e32 v4, v9, v4
	v_sub_f32_e32 v3, v3, v8
	v_sub_f32_e32 v5, v5, v7
	v_add_f32_e32 v3, v5, v3
	v_add_f32_e32 v5, v4, v2
	v_sub_f32_e32 v7, v5, v4
	v_sub_f32_e32 v8, v5, v7
	v_sub_f32_e32 v4, v4, v8
	v_sub_f32_e32 v2, v2, v7
	v_add_f32_e32 v3, v5, v3
	v_add_f32_e32 v2, v2, v4
	v_add_f32_e32 v4, v6, v3
	v_sub_f32_e32 v5, v4, v6
	v_sub_f32_e32 v3, v3, v5
	v_add_f32_e32 v2, v2, v3
	s_mov_b32 s17, 0x7f800000
	v_add_f32_e32 v2, v4, v2
	v_cmp_neq_f32_e32 vcc, s17, v1
	s_mov_b32 s17, 0x33800000
	v_add_u32_e32 v111, 0x4400, v110
	v_cndmask_b32_e32 v2, v223, v2, vcc
	v_cmp_lt_f32_e64 vcc, |v1|, s17
	s_ashr_i32 s17, s16, 31
	s_lshl_b64 s[16:17], s[16:17], 1
	v_cndmask_b32_e32 v1, v2, v1, vcc
	v_mul_f32_e32 v1, 0xc1000000, v1
	v_mul_f32_e32 v109, 0x3fb8aa3b, v1
	v_lshl_add_u64 v[54:55], v[156:157], 0, s[16:17]
	v_mov_b32_e32 v56, v53
	v_mov_b32_e32 v57, v52
	v_lshl_add_u64 v[58:59], v[158:159], 0, s[16:17]
	v_lshl_add_u64 v[60:61], v[164:165], 0, s[16:17]
	s_mov_b64 s[60:61], 0
	v_mov_b32_e32 v62, v214
	s_and_b32 s100, s2, 7
	s_lshl_b32 s100, s100, 23
	s_add_u32 s100, s100, s16
	s_add_u32 s98, s86, s100
	s_addc_u32 s99, s87, 0
	s_add_u32 s98, s98, 0x13ffe800
	s_addc_u32 s99, s99, 0
	v_lshrrev_b32_e32 v249, 4, v160
	v_and_b32_e32 v248, 15, v160
	v_lshlrev_b32_e32 v248, 4, v248
	v_lshl_add_u32 v248, v249, 11, v248
	v_lshrrev_b32_e32 v249, 6, v160
	s_nop 0
	v_readfirstlane_b32 s100, v249
	s_nop 3
	s_lshl_b32 s100, s100, 10
	s_add_u32 m0, s100, 0x16000
	s_mov_b32 s100, s98
	s_mov_b32 s101, s99
	global_load_lds_dwordx4 v248, s[100:101]
	s_add_u32 s100, s100, 0x10000
	s_addc_u32 s101, s101, 0
	s_add_u32 m0, m0, 0x2000
	s_nop 0
	global_load_lds_dwordx4 v248, s[100:101]
	s_cmp_eq_u32 m0, 0x18000
	s_cbranch_scc0 .Llru_dma_skip_L0p
	s_add_u32 s100, s100, 0x10000
	s_addc_u32 s101, s101, 0
	s_add_u32 m0, m0, 0x2000
	s_nop 0
	global_load_lds_dwordx4 v248, s[100:101]
.Llru_dma_skip_L0p:
	s_waitcnt vmcnt(0)
	s_barrier
	s_branch .LBB0_248

; __device__ __forceinline__ unsigned cvt_pk_bf16(float lo, float hi) { const f32x2 v = {lo, hi}; return __builtin_bit_cast(unsigned, __builtin_convertvector(v, bf16x2v)); }
; __device__ __forceinline__ void lru_item(LAS unsigned char* lds, const Params& P, int l, int b, int g) {
;     ...
;         const int sbase = ch * 64 + 16 * sc;
;         float xrv[19]; unsigned short grv[16];
; #pragma unroll
;         for (int i = 0; i < 19; ++i) { const int s = sbase - 3 + i; xrv[i] = (s >= 0) ? bf2f(XR[(rowb + (s >= 0 ? s : 0)) * DM + c0 + c]) : 0.f; }
; #pragma unroll
;         for (int i = 0; i < 16; ++i) grv[i] = GR[(rowb + sbase + i) * DM + c0 + c];
;         float xbv[16];
; #pragma unroll
;         for (int i = 0; i < 16; ++i) { xbv[i] = cb + cw0 * xrv[i] + cw1 * xrv[i + 1] + cw2 * xrv[i + 2] + cw3 * xrv[i + 3];
;             Abf[(16 * sc + i) * 136 + c] = (bf16_t)(cvt_pk_bf16(xbv[i], 0.f) & 0xffffu); }
.LBB0_248:
	v_add_u32_e32 v1, s60, v162
	v_cmp_eq_u32_e64 s[16:17], 0, v1
	v_and_b32_e32 v248, 0x7f, v160
	v_lshrrev_b32_e32 v249, 7, v160
	v_lshlrev_b32_e32 v248, 1, v248
	v_lshl_add_u32 v248, v249, 12, v248
	v_add_u32_e32 v248, 0x16000, v248
	ds_read_u16 v4, v248
	ds_read_u16 v5, v248 offset:256
	ds_read_u16 v7, v248 offset:512
	ds_read_u16 v13, v248 offset:1280
	ds_read_u16 v14, v248 offset:1536
	ds_read_u16 v15, v248 offset:1792
	ds_read_u16 v16, v248 offset:2048
	ds_read_u16 v17, v248 offset:2304
	ds_read_u16 v66, v248 offset:2560
	v_lshl_add_u64 v[64:65], v[60:61], 0, s[60:61]
	v_add_co_u32_e32 v8, vcc, 0x18000000, v64
	s_nop 0
	v_addc_co_u32_e32 v9, vcc, 0, v65, vcc
	global_load_ushort v126, v[8:9], off
	global_load_ushort v125, v[8:9], off offset:2048
	v_add_co_u32_e32 v8, vcc, 0x18001000, v64
	v_lshl_add_u64 v[2:3], v[58:59], 0, s[60:61]
	s_nop 0
	v_addc_co_u32_e32 v9, vcc, 0, v65, vcc
	global_load_ushort v124, v[8:9], off
	global_load_ushort v123, v[8:9], off offset:2048
	v_add_co_u32_e32 v8, vcc, 0x18002000, v64
	s_brev_b32 s1, 40
	s_nop 0
	v_addc_co_u32_e32 v9, vcc, 0, v65, vcc
	global_load_ushort v122, v[8:9], off
	global_load_ushort v121, v[8:9], off offset:2048
	v_add_co_u32_e32 v8, vcc, 0x18003000, v64
	s_nop 1
	v_addc_co_u32_e32 v9, vcc, 0, v65, vcc
	global_load_ushort v120, v[8:9], off
	global_load_ushort v119, v[8:9], off offset:2048
	v_add_co_u32_e32 v8, vcc, 0x18004000, v64
	s_nop 1
	v_addc_co_u32_e32 v9, vcc, 0, v65, vcc
	global_load_ushort v118, v[8:9], off
	global_load_ushort v117, v[8:9], off offset:2048
	v_add_co_u32_e32 v8, vcc, 0x18005000, v64
	s_nop 1
	v_addc_co_u32_e32 v9, vcc, 0, v65, vcc
	global_load_ushort v116, v[8:9], off
	global_load_ushort v115, v[8:9], off offset:2048
	v_add_co_u32_e32 v8, vcc, 0x18006000, v64
	s_nop 1
	v_addc_co_u32_e32 v9, vcc, 0, v65, vcc
	global_load_ushort v114, v[8:9], off
	global_load_ushort v113, v[8:9], off offset:2048
	v_add_co_u32_e32 v8, vcc, 0x18007000, v64
	s_nop 1
	v_addc_co_u32_e32 v9, vcc, 0, v65, vcc
	global_load_ushort v112, v[8:9], off
	global_load_ushort v63, v[8:9], off offset:2048
	s_waitcnt lgkmcnt(6)
	ds_read_u16 v70, v248 offset:2816
	ds_read_u16 v71, v248 offset:3072
	ds_read_u16 v72, v248 offset:3328
	ds_read_u16 v73, v248 offset:3584
	ds_read_u16 v74, v248 offset:3840
	ds_read_u16 v75, v248 offset:4096
	ds_read_u16 v83, v248 offset:4352
	ds_read_u16 v82, v248 offset:4608
	s_waitcnt lgkmcnt(0)
	v_lshlrev_b32_e32 v4, 16, v4
	v_lshlrev_b32_e32 v5, 16, v5
	v_lshlrev_b32_e32 v7, 16, v7
	v_cndmask_b32_e64 v4, v4, 0, s[16:17]
	v_cndmask_b32_e64 v5, v5, 0, s[16:17]
	v_cndmask_b32_e64 v7, v7, 0, s[16:17]
	v_mov_b32_e32 v6, v5
	v_pk_mul_f32 v[8:9], v[50:51], v[4:5]
	v_pk_mul_f32 v[4:5], v[50:51], v[6:7]
	v_add_f32_e32 v1, v106, v8
	v_add_f32_e32 v4, v106, v4
	v_add_f32_e32 v12, v4, v5
	v_add_co_u32_e32 v4, vcc, s1, v2
	s_mov_b32 s1, 0x14001000
	s_nop 0
	v_addc_co_u32_e32 v5, vcc, 0, v3, vcc
	v_add_co_u32_e32 v8, vcc, s1, v2
	v_add_f32_e32 v1, v1, v9
	s_nop 0
	v_addc_co_u32_e32 v9, vcc, 0, v3, vcc
	ds_read_u16 v6, v248 offset:768
	s_nop 0
	ds_read_u16 v4, v248 offset:1024
	s_nop 0
	s_mov_b32 s1, 0x14002000
	v_add_co_u32_e32 v8, vcc, s1, v2
	s_mov_b32 s1, 0x14003000
	s_nop 0
	v_addc_co_u32_e32 v9, vcc, 0, v3, vcc
	s_waitcnt lgkmcnt(0)
	v_lshlrev_b32_e32 v5, 16, v4
	v_lshlrev_b32_e32 v4, 16, v6
	v_mov_b32_e32 v6, v7
	v_mov_b32_e32 v7, v4
	v_pk_mul_f32 v[10:11], v[56:57], v[6:7]
	v_pk_mul_f32 v[6:7], v[50:51], v[6:7]
	v_add_f32_e32 v1, v1, v10
	v_add_co_u32_e32 v10, vcc, s1, v2
	v_add_f32_e32 v67, v1, v11
	s_nop 0
	v_addc_co_u32_e32 v11, vcc, 0, v3, vcc
	s_mov_b32 s1, 0x14004000
	v_add_co_u32_e32 v8, vcc, s1, v2
	s_mov_b32 s1, 0x14005000
	s_nop 0
	v_addc_co_u32_e32 v9, vcc, 0, v3, vcc
	v_add_co_u32_e32 v10, vcc, s1, v2
	s_mov_b32 s1, 0x14006000
	s_nop 0
	v_addc_co_u32_e32 v11, vcc, 0, v3, vcc
	v_add_co_u32_e32 v8, vcc, s1, v2
	s_mov_b32 s1, 0x14007000
	s_nop 0
	v_addc_co_u32_e32 v9, vcc, 0, v3, vcc
	v_add_co_u32_e32 v2, vcc, s1, v2
	v_cvt_pk_bf16_f32 v1, v67, s0
	s_nop 0
	v_addc_co_u32_e32 v3, vcc, 0, v3, vcc
	v_pk_mul_f32 v[2:3], v[56:57], v[4:5]
	ds_write_b16 v218, v1
	v_add_f32_e32 v1, v12, v2
	v_add_f32_e32 v2, v106, v6
	v_add_f32_e32 v2, v2, v7
	v_pk_mul_f32 v[6:7], v[50:51], v[4:5]
	v_mov_b32_e32 v9, v5
	v_add_f32_e32 v6, v106, v6
	v_add_f32_e32 v12, v6, v7
	v_lshlrev_b32_e32 v7, 16, v14
	v_lshlrev_b32_e32 v6, 16, v13
	v_pk_mov_b32 v[4:5], v[4:5], v[6:7] op_sel:[1,0]
	v_mov_b32_e32 v8, v6
	v_pk_mul_f32 v[4:5], v[50:51], v[4:5]
	v_pk_mul_f32 v[8:9], v[52:53], v[8:9]
	v_pk_mul_f32 v[10:11], v[56:57], v[6:7]
	v_add_f32_e32 v4, v106, v4
	v_add_f32_e32 v2, v9, v2
	v_add_f32_e32 v9, v10, v12
	v_add_f32_e32 v10, v4, v5
	v_pk_mul_f32 v[4:5], v[50:51], v[6:7]
	v_mov_b32_e32 v13, v7
	v_add_f32_e32 v4, v106, v4
	v_add_f32_e32 v68, v4, v5
	v_add_f32_e32 v90, v11, v9
	v_add_f32_e32 v92, v8, v2
	v_add_f32_e32 v94, v3, v1
	v_cvt_pk_bf16_f32 v2, v92, s0
	v_cvt_pk_bf16_f32 v1, v94, s0
	ds_write_b16 v219, v2 offset:272
	ds_write_b16 v219, v1
	s_and_b32 s1, s0, 0x80
	v_lshlrev_b32_e32 v4, 16, v15
	v_lshlrev_b32_e32 v5, 16, v16
	v_pk_mov_b32 v[6:7], v[6:7], v[4:5] op_sel:[1,0]
	v_mov_b32_e32 v12, v4
	v_pk_mul_f32 v[6:7], v[50:51], v[6:7]
	v_pk_mul_f32 v[12:13], v[52:53], v[12:13]
	v_pk_mul_f32 v[14:15], v[56:57], v[4:5]
	v_add_f32_e32 v6, v106, v6
	v_add_f32_e32 v10, v13, v10
	v_add_f32_e32 v13, v14, v68
	v_add_f32_e32 v14, v6, v7
	v_pk_mul_f32 v[6:7], v[50:51], v[4:5]
	v_add_f32_e32 v86, v15, v13
	v_add_f32_e32 v6, v106, v6
	v_add_f32_e32 v76, v6, v7
	v_lshlrev_b32_e32 v7, 16, v66
	v_lshlrev_b32_e32 v6, 16, v17
	v_mov_b32_e32 v17, v5
	v_pk_mov_b32 v[4:5], v[4:5], v[6:7] op_sel:[1,0]
; #define LAS __attribute__((address_space(3)))
; __device__ __forceinline__ unsigned cvt_pk_bf16(float lo, float hi) { const f32x2 v = {lo, hi}; return __builtin_bit_cast(unsigned, __builtin_convertvector(v, bf16x2v)); }
; __device__ __forceinline__ f32x16 mfma32(bf16x8 a, bf16x8 b, f32x16 c) { return __builtin_amdgcn_mfma_f32_32x32x16_bf16(a, b, c, 0, 0, 0); }
; __device__ __forceinline__ void lru_item(LAS unsigned char* lds, const Params& P, int l, int b, int g) {
;     ...
;         float xbv[16];
; #pragma unroll
;         for (int i = 0; i < 16; ++i) { xbv[i] = cb + cw0 * xrv[i] + cw1 * xrv[i + 1] + cw2 * xrv[i + 2] + cw3 * xrv[i + 3];
;             Abf[(16 * sc + i) * 136 + c] = (bf16_t)(cvt_pk_bf16(xbv[i], 0.f) & 0xffffu); }
;         __syncthreads();
; #pragma unroll
;         for (int mb = 0; mb < 2; ++mb) { f32x16 acc;
; #pragma unroll
;             for (int i = 0; i < 16; ++i) acc[i] = 0.f;
; #pragma unroll
;             for (int kk = 0; kk < 8; ++kk) { const bf16x8 af = *(const LAS bf16x8*)((LAS unsigned char*)Abf + (32 * mb + r) * 272 + (16 * kk + 8 * hh) * 2); acc = mfma32(af, bfr[kk], acc); }
; #pragma unroll
;             for (int i = 0; i < 16; ++i) G[(32 * mb + (i & 3) + 8 * (i >> 2) + 4 * hh) * 260 + 32 * w + r] = acc[i]; }
	v_mov_b32_e32 v16, v6
	v_pk_mul_f32 v[4:5], v[50:51], v[4:5]
	v_pk_mul_f32 v[16:17], v[52:53], v[16:17]
	v_add_f32_e32 v4, v106, v4
	v_add_f32_e32 v66, v4, v5
	v_pk_mul_f32 v[4:5], v[50:51], v[6:7]
	v_pk_mul_f32 v[68:69], v[56:57], v[6:7]
	v_add_f32_e32 v4, v106, v4
	v_add_f32_e32 v14, v17, v14
	v_add_f32_e32 v17, v68, v76
	v_add_f32_e32 v68, v4, v5
	v_lshlrev_b32_e32 v5, 16, v71
	v_lshlrev_b32_e32 v4, 16, v70
	v_mov_b32_e32 v71, v7
	v_pk_mov_b32 v[6:7], v[6:7], v[4:5] op_sel:[1,0]
	v_mov_b32_e32 v70, v4
	v_pk_mul_f32 v[6:7], v[50:51], v[6:7]
	v_pk_mul_f32 v[78:79], v[52:53], v[70:71]
	v_add_f32_e32 v6, v106, v6
	v_add_f32_e32 v79, v79, v66
	v_add_f32_e32 v66, v6, v7
	v_pk_mul_f32 v[6:7], v[50:51], v[4:5]
	v_pk_mul_f32 v[70:71], v[56:57], v[4:5]
	v_add_f32_e32 v6, v106, v6
	v_add_f32_e32 v84, v70, v68
	v_add_f32_e32 v68, v6, v7
	v_lshlrev_b32_e32 v7, 16, v73
	v_lshlrev_b32_e32 v6, 16, v72
	v_mov_b32_e32 v73, v5
	v_pk_mov_b32 v[4:5], v[4:5], v[6:7] op_sel:[1,0]
	v_mov_b32_e32 v72, v6
	v_pk_mul_f32 v[4:5], v[50:51], v[4:5]
	v_pk_mul_f32 v[76:77], v[52:53], v[72:73]
	v_add_f32_e32 v4, v106, v4
	v_add_f32_e32 v77, v77, v66
	v_add_f32_e32 v66, v4, v5
	v_pk_mul_f32 v[4:5], v[50:51], v[6:7]
	v_pk_mul_f32 v[72:73], v[56:57], v[6:7]
	v_add_f32_e32 v4, v106, v4
	v_add_f32_e32 v85, v72, v68
	v_add_f32_e32 v68, v4, v5
	v_lshlrev_b32_e32 v5, 16, v75
	v_lshlrev_b32_e32 v4, 16, v74
	v_mov_b32_e32 v75, v7
	v_pk_mov_b32 v[6:7], v[6:7], v[4:5] op_sel:[1,0]
	v_mov_b32_e32 v74, v4
	v_pk_mul_f32 v[6:7], v[50:51], v[6:7]
	v_pk_mul_f32 v[74:75], v[52:53], v[74:75]
	v_add_f32_e32 v6, v106, v6
	v_add_f32_e32 v72, v75, v66
	v_add_f32_e32 v66, v6, v7
	v_pk_mul_f32 v[6:7], v[50:51], v[4:5]
	v_pk_mul_f32 v[80:81], v[56:57], v[4:5]
	v_add_f32_e32 v4, v106, v6
	v_add_f32_e32 v70, v80, v68
	v_add_f32_e32 v68, v4, v7
	v_lshlrev_b32_e32 v7, 16, v83
	v_mov_b32_e32 v4, v7
	v_lshlrev_b32_e32 v6, 16, v82
	v_pk_mul_f32 v[4:5], v[52:53], v[4:5]
	v_pk_mul_f32 v[6:7], v[52:53], v[6:7]
	v_add_f32_e32 v5, v5, v66
	v_add_f32_e32 v7, v7, v68
	v_add_f32_e32 v68, v4, v5
	v_cvt_pk_bf16_f32 v4, v68, s0
	v_add_f32_e32 v70, v81, v70
	ds_write_b16 v219, v4 offset:3536
	v_cvt_pk_bf16_f32 v4, v70, s0
	v_add_f32_e32 v72, v74, v72
	ds_write_b16 v219, v4 offset:3264
	v_cvt_pk_bf16_f32 v4, v72, s0
	v_add_f32_e32 v74, v73, v85
	ds_write_b16 v219, v4 offset:2992
	v_cvt_pk_bf16_f32 v4, v74, s0
	v_add_f32_e32 v76, v76, v77
	ds_write_b16 v219, v4 offset:2720
	v_cvt_pk_bf16_f32 v4, v76, s0
	v_add_f32_e32 v80, v71, v84
	ds_write_b16 v219, v4 offset:2448
	v_cvt_pk_bf16_f32 v4, v80, s0
	v_add_f32_e32 v82, v78, v79
	ds_write_b16 v219, v4 offset:2176
	v_cvt_pk_bf16_f32 v4, v82, s0
	v_add_f32_e32 v78, v69, v17
	ds_write_b16 v219, v4 offset:1904
	v_cvt_pk_bf16_f32 v4, v78, s0
	v_add_f32_e32 v84, v16, v14
	ds_write_b16 v219, v4 offset:1632
	v_cvt_pk_bf16_f32 v4, v84, s0
	ds_write_b16 v219, v4 offset:1360
	v_cvt_pk_bf16_f32 v4, v86, s0
	v_add_f32_e32 v88, v12, v10
	v_add_f32_e32 v66, v6, v7
	ds_write_b16 v219, v4 offset:1088
	v_cvt_pk_bf16_f32 v4, v88, s0
	v_cvt_pk_bf16_f32 v6, v66, s0
	ds_write_b16 v219, v4 offset:816
	v_cvt_pk_bf16_f32 v4, v90, s0
	ds_write_b16 v219, v6 offset:3808
	ds_write_b16 v219, v4 offset:544
	s_waitcnt lgkmcnt(0)
	s_barrier
	v_lshrrev_b32_e32 v249, 4, v160
	v_and_b32_e32 v248, 15, v160
	v_lshlrev_b32_e32 v248, 4, v248
	v_lshl_add_u32 v248, v249, 11, v248
	v_lshrrev_b32_e32 v249, 6, v160
	s_nop 0
	v_readfirstlane_b32 s100, v249
	s_nop 3
	s_lshl_b32 s100, s100, 10
	s_add_u32 m0, s100, 0x16000
	s_add_u32 s100, s98, s60
	s_addc_u32 s101, s99, s61
	s_add_u32 s100, s100, 0x20000
	s_addc_u32 s101, s101, 0
	global_load_lds_dwordx4 v248, s[100:101]
	s_add_u32 s100, s100, 0x10000
	s_addc_u32 s101, s101, 0
	s_add_u32 m0, m0, 0x2000
	s_nop 0
	global_load_lds_dwordx4 v248, s[100:101]
	s_cmp_eq_u32 m0, 0x18000
	s_cbranch_scc0 .Llru_dma_skip_L0
	s_add_u32 s100, s100, 0x10000
	s_addc_u32 s101, s101, 0
	s_add_u32 m0, m0, 0x2000
	s_nop 0
	global_load_lds_dwordx4 v248, s[100:101]
.Llru_dma_skip_L0:
	ds_read_b128 v[2:5], v220
	ds_read_b128 v[96:99], v220 offset:32
	s_waitcnt lgkmcnt(1)
	v_mfma_f32_32x32x16_bf16 v[2:17], v[2:5], v[18:21], 0
	s_waitcnt lgkmcnt(0)
	v_mfma_f32_32x32x16_bf16 v[2:17], v[96:99], v[22:25], v[2:17]
	ds_read_b128 v[96:99], v220 offset:64
	s_waitcnt lgkmcnt(0)
	v_mfma_f32_32x32x16_bf16 v[2:17], v[96:99], v[26:29], v[2:17]
	ds_read_b128 v[96:99], v220 offset:96
	s_waitcnt lgkmcnt(0)
	v_mfma_f32_32x32x16_bf16 v[2:17], v[96:99], v[30:33], v[2:17]
	ds_read_b128 v[96:99], v220 offset:128
	s_waitcnt lgkmcnt(0)
	v_mfma_f32_32x32x16_bf16 v[2:17], v[96:99], v[34:37], v[2:17]
	ds_read_b128 v[96:99], v220 offset:160
	s_waitcnt lgkmcnt(0)
	v_mfma_f32_32x32x16_bf16 v[2:17], v[96:99], v[38:41], v[2:17]
	ds_read_b128 v[96:99], v220 offset:192
	s_waitcnt lgkmcnt(0)
	v_mfma_f32_32x32x16_bf16 v[2:17], v[96:99], v[42:45], v[2:17]
	ds_read_b128 v[96:99], v220 offset:224
	s_waitcnt lgkmcnt(0)
	v_mfma_f32_32x32x16_bf16 v[2:17], v[96:99], v[46:49], v[2:17]
	s_nop 11
	ds_write_b32 v110, v2 offset:17408
	ds_write_b32 v110, v3 offset:18448
	ds_write_b32 v110, v4 offset:19488
	ds_write_b32 v110, v5 offset:20528
	ds_write_b32 v110, v6 offset:25728
	ds_write_b32 v110, v7 offset:26768
	ds_write_b32 v110, v8 offset:27808
	ds_write_b32 v110, v9 offset:28848
	ds_write_b32 v110, v10 offset:34048
	ds_write_b32 v110, v11 offset:35088
	ds_write_b32 v110, v12 offset:36128
	ds_write_b32 v110, v13 offset:37168
	ds_write_b32 v110, v14 offset:42368
	ds_write_b32 v110, v15 offset:43408
	ds_write_b32 v110, v16 offset:44448
	ds_write_b32 v110, v17 offset:45488
	ds_read_b128 v[2:5], v220 offset:8704
	ds_read_b128 v[96:99], v220 offset:8736
	s_waitcnt lgkmcnt(1)
; #define LAS __attribute__((address_space(3)))
; __device__ __forceinline__ float fexp2(float x) { return __builtin_amdgcn_exp2f(x); }
; __device__ __forceinline__ float sigmoidf_(float x) { return frcp(1.0f + fexp2(-x * LOG2E)); }
; __device__ __forceinline__ f32x16 mfma32(bf16x8 a, bf16x8 b, f32x16 c) { return __builtin_amdgcn_mfma_f32_32x32x16_bf16(a, b, c, 0, 0, 0); }
; __device__ __forceinline__ void lru_item(LAS unsigned char* lds, const Params& P, int l, int b, int g) {
;     ...
;         for (int mb = 0; mb < 2; ++mb) { f32x16 acc;
; #pragma unroll
;             for (int i = 0; i < 16; ++i) acc[i] = 0.f;
; #pragma unroll
;             for (int kk = 0; kk < 8; ++kk) { const bf16x8 af = *(const LAS bf16x8*)((LAS unsigned char*)Abf + (32 * mb + r) * 272 + (16 * kk + 8 * hh) * 2); acc = mfma32(af, bfr[kk], acc); }
; #pragma unroll
;             for (int i = 0; i < 16; ++i) G[(32 * mb + (i & 3) + 8 * (i >> 2) + 4 * hh) * 260 + 32 * w + r] = acc[i]; }
;         __syncthreads();
;         float hloc[16], pv[16]; float hl = 0.f, pp = 1.f;
; #pragma unroll
;         for (int i = 0; i < 16; ++i) { const float rp = G[(16 * sc + i) * 260 + c] + ba, ip = G[(16 * sc + i) * 260 + 128 + c] + bx;
;             const float rr = sigmoidf_(rp), ii = sigmoidf_(ip); const float a = fexp2(rr * nsp8);
;             const float mult = (sbase + i == 0) ? 1.0f : sqrtf(fmaxf(1.0f - a * a, 0.f));
;             const float u = mult * (ii * xbv[i]);
;             hl = a * hl + u; pp *= a; hloc[i] = hl; pv[i] = pp; }
	v_mfma_f32_32x32x16_bf16 v[2:17], v[2:5], v[18:21], 0
	s_waitcnt lgkmcnt(0)
	v_mfma_f32_32x32x16_bf16 v[2:17], v[96:99], v[22:25], v[2:17]
	ds_read_b128 v[96:99], v220 offset:8768
	s_waitcnt lgkmcnt(0)
	v_mfma_f32_32x32x16_bf16 v[2:17], v[96:99], v[26:29], v[2:17]
	ds_read_b128 v[96:99], v220 offset:8800
	s_waitcnt lgkmcnt(0)
	v_mfma_f32_32x32x16_bf16 v[2:17], v[96:99], v[30:33], v[2:17]
	ds_read_b128 v[96:99], v220 offset:8832
	s_waitcnt lgkmcnt(0)
	v_mfma_f32_32x32x16_bf16 v[2:17], v[96:99], v[34:37], v[2:17]
	ds_read_b128 v[96:99], v220 offset:8864
	s_waitcnt lgkmcnt(0)
	v_mfma_f32_32x32x16_bf16 v[2:17], v[96:99], v[38:41], v[2:17]
	ds_read_b128 v[96:99], v220 offset:8896
	s_waitcnt lgkmcnt(0)
	v_mfma_f32_32x32x16_bf16 v[2:17], v[96:99], v[42:45], v[2:17]
	ds_read_b128 v[96:99], v220 offset:8928
	s_waitcnt lgkmcnt(0)
	v_mfma_f32_32x32x16_bf16 v[2:17], v[96:99], v[46:49], v[2:17]
	s_nop 11
	ds_write_b32 v110, v2 offset:50688
	ds_write_b32 v110, v3 offset:51728
	ds_write_b32 v110, v4 offset:52768
	ds_write_b32 v110, v5 offset:53808
	ds_write_b32 v110, v6 offset:59008
	ds_write_b32 v110, v7 offset:60048
	ds_write_b32 v110, v8 offset:61088
	ds_write_b32 v110, v9 offset:62128
	ds_write_b32 v111, v10 offset:49920
	ds_write_b32 v111, v11 offset:50960
	ds_write_b32 v111, v12 offset:52000
	ds_write_b32 v111, v13 offset:53040
	ds_write_b32 v111, v14 offset:58240
	ds_write_b32 v111, v15 offset:59280
	ds_write_b32 v111, v16 offset:60320
	ds_write_b32 v111, v17 offset:61360
	s_waitcnt lgkmcnt(0)
	s_barrier
	ds_read2st64_b32 v[2:3], v195 offset0:68 offset1:70
	s_waitcnt lgkmcnt(0)
	v_add_f32_e32 v1, v107, v2
	v_mul_f32_e32 v1, 0xbfb8aa3b, v1
	v_exp_f32_e32 v1, v1
	v_add_f32_e32 v2, v108, v3
	v_mul_f32_e32 v2, 0xbfb8aa3b, v2
	v_exp_f32_e32 v2, v2
	v_add_f32_e32 v1, 1.0, v1
	v_rcp_f32_e32 v1, v1
	v_add_f32_e32 v2, 1.0, v2
	v_rcp_f32_e32 v3, v2
	v_mul_f32_e32 v1, v109, v1
	v_exp_f32_e32 v2, v1
	v_mul_f32_e32 v3, v67, v3
	v_fma_f32 v1, -v2, v2, 1.0
	v_max_f32_e32 v1, 0, v1
	v_cmp_gt_f32_e32 vcc, s79, v1
	v_mul_f32_e32 v4, 0x4f800000, v1
	s_nop 0
	v_cndmask_b32_e32 v1, v1, v4, vcc
	v_sqrt_f32_e32 v4, v1
	s_nop 0
	v_add_u32_e32 v5, -1, v4
	v_fma_f32 v6, -v5, v4, v1
	v_cmp_ge_f32_e64 s[18:19], 0, v6
	v_add_u32_e32 v6, 1, v4
	s_nop 0
	v_cndmask_b32_e64 v5, v4, v5, s[18:19]
	v_fma_f32 v4, -v6, v4, v1
	v_cmp_lt_f32_e64 s[18:19], 0, v4
	s_nop 1
	v_cndmask_b32_e64 v4, v5, v6, s[18:19]
	v_mul_f32_e32 v5, 0x37800000, v4
	ds_read2st64_b32 v[6:7], v196 offset0:68 offset1:70
	v_cndmask_b32_e32 v4, v4, v5, vcc
	v_cmp_class_f32_e32 vcc, v1, v215
	s_nop 1
	v_cndmask_b32_e32 v1, v4, v1, vcc
	v_cndmask_b32_e64 v1, v1, 1.0, s[16:17]
	v_mul_f32_e32 v4, v3, v1
	v_pk_fma_f32 v[4:5], v[2:3], v[0:1], v[4:5] op_sel_hi:[1,1,0]
	s_waitcnt lgkmcnt(0)
	v_add_f32_e32 v1, v107, v6
	v_mul_f32_e32 v1, 0xbfb8aa3b, v1
	v_exp_f32_e32 v1, v1
	v_add_f32_e32 v3, v108, v7
	v_mul_f32_e32 v3, 0xbfb8aa3b, v3
	v_exp_f32_e32 v3, v3
	v_add_f32_e32 v1, 1.0, v1
	v_rcp_f32_e32 v1, v1
	v_mov_b32_e32 v95, v4
	v_add_f32_e32 v3, 1.0, v3
	v_rcp_f32_e32 v8, v3
	v_mul_f32_e32 v1, v109, v1
	v_exp_f32_e32 v9, v1
	s_nop 0
	v_fma_f32 v1, -v9, v9, 1.0
	v_max_f32_e32 v1, 0, v1
	v_cmp_gt_f32_e32 vcc, s79, v1
	v_mul_f32_e32 v3, 0x4f800000, v1
	s_nop 0
	v_cndmask_b32_e32 v1, v1, v3, vcc
	v_sqrt_f32_e32 v3, v1
	s_nop 0
	v_add_u32_e32 v5, -1, v3
	v_fma_f32 v6, -v5, v3, v1
	v_cmp_ge_f32_e64 s[16:17], 0, v6
	v_add_u32_e32 v6, 1, v3
	s_nop 0
	v_cndmask_b32_e64 v5, v3, v5, s[16:17]
	v_fma_f32 v3, -v6, v3, v1
	v_cmp_lt_f32_e64 s[16:17], 0, v3
	s_nop 1
	v_cndmask_b32_e64 v3, v5, v6, s[16:17]
	v_mul_f32_e32 v5, 0x37800000, v3
	v_cndmask_b32_e32 v3, v3, v5, vcc
	v_cmp_class_f32_e32 vcc, v1, v215
	v_pk_mul_f32 v[6:7], v[94:95], v[8:9]
	s_nop 0
	v_cndmask_b32_e32 v1, v3, v1, vcc
	v_fmac_f32_e32 v7, v6, v1
	v_mul_f32_e32 v1, v2, v9
	ds_read2st64_b32 v[8:9], v197 offset0:68 offset1:70
	v_mov_b32_e32 v93, v7
	s_waitcnt lgkmcnt(0)
	v_add_f32_e32 v3, v107, v8
	v_mul_f32_e32 v3, 0xbfb8aa3b, v3
	v_exp_f32_e32 v3, v3
	v_add_f32_e32 v5, v108, v9
	v_mul_f32_e32 v5, 0xbfb8aa3b, v5
	v_exp_f32_e32 v5, v5
	v_add_f32_e32 v3, 1.0, v3
	v_rcp_f32_e32 v3, v3
	v_add_f32_e32 v5, 1.0, v5
	v_rcp_f32_e32 v10, v5
	v_mul_f32_e32 v3, v109, v3
	v_exp_f32_e32 v11, v3
	s_nop 0
	v_fma_f32 v3, -v11, v11, 1.0
	v_max_f32_e32 v3, 0, v3
	v_cmp_gt_f32_e32 vcc, s79, v3
	v_mul_f32_e32 v5, 0x4f800000, v3
	s_nop 0
	v_cndmask_b32_e32 v3, v3, v5, vcc
	v_sqrt_f32_e32 v5, v3
	s_nop 0
	v_add_u32_e32 v6, -1, v5
	v_fma_f32 v8, -v6, v5, v3
	v_cmp_ge_f32_e64 s[16:17], 0, v8
	v_add_u32_e32 v8, 1, v5
	s_nop 0
	v_cndmask_b32_e64 v6, v5, v6, s[16:17]
	v_fma_f32 v5, -v8, v5, v3
	v_cmp_lt_f32_e64 s[16:17], 0, v5
	s_nop 1
	v_cndmask_b32_e64 v5, v6, v8, s[16:17]
	v_mul_f32_e32 v6, 0x37800000, v5
	v_cndmask_b32_e32 v5, v5, v6, vcc
	v_cmp_class_f32_e32 vcc, v3, v215
	v_pk_mul_f32 v[8:9], v[92:93], v[10:11]
	s_nop 0
	v_cndmask_b32_e32 v3, v5, v3, vcc
	v_fmac_f32_e32 v9, v8, v3
	v_mul_f32_e32 v3, v1, v11
	ds_read2st64_b32 v[10:11], v198 offset0:68 offset1:70
	v_mov_b32_e32 v91, v9
	s_waitcnt lgkmcnt(0)
	v_add_f32_e32 v5, v107, v10
	v_mul_f32_e32 v5, 0xbfb8aa3b, v5
	v_exp_f32_e32 v5, v5
	v_add_f32_e32 v6, v108, v11
	v_mul_f32_e32 v6, 0xbfb8aa3b, v6
	v_exp_f32_e32 v6, v6
	v_add_f32_e32 v5, 1.0, v5
	v_rcp_f32_e32 v5, v5
	v_add_f32_e32 v6, 1.0, v6
	v_rcp_f32_e32 v12, v6
	v_mul_f32_e32 v5, v109, v5
	v_exp_f32_e32 v13, v5
	s_nop 0
	v_fma_f32 v5, -v13, v13, 1.0
	v_max_f32_e32 v5, 0, v5
	v_cmp_gt_f32_e32 vcc, s79, v5
	v_mul_f32_e32 v6, 0x4f800000, v5
	s_nop 0
	v_cndmask_b32_e32 v5, v5, v6, vcc
	v_sqrt_f32_e32 v6, v5
	s_nop 0
	v_add_u32_e32 v8, -1, v6
	v_fma_f32 v10, -v8, v6, v5
	v_cmp_ge_f32_e64 s[16:17], 0, v10
	v_add_u32_e32 v10, 1, v6
	s_nop 0
	v_cndmask_b32_e64 v8, v6, v8, s[16:17]
	v_fma_f32 v6, -v10, v6, v5
	v_cmp_lt_f32_e64 s[16:17], 0, v6
	s_nop 1
	v_cndmask_b32_e64 v6, v8, v10, s[16:17]
	v_mul_f32_e32 v8, 0x37800000, v6
	v_cndmask_b32_e32 v6, v6, v8, vcc
	v_cmp_class_f32_e32 vcc, v5, v215
	v_pk_mul_f32 v[10:11], v[90:91], v[12:13]
	s_nop 0
	v_cndmask_b32_e32 v5, v6, v5, vcc
	v_fmac_f32_e32 v11, v10, v5
	v_mul_f32_e32 v5, v3, v13
	ds_read2st64_b32 v[12:13], v199 offset0:68 offset1:70
	v_mov_b32_e32 v89, v11
	s_waitcnt lgkmcnt(0)
; __device__ __forceinline__ float fexp2(float x) { return __builtin_amdgcn_exp2f(x); }
; __device__ __forceinline__ float sigmoidf_(float x) { return frcp(1.0f + fexp2(-x * LOG2E)); }
; __device__ __forceinline__ void lru_item(LAS unsigned char* lds, const Params& P, int l, int b, int g) {
;     ...
;         float hloc[16], pv[16]; float hl = 0.f, pp = 1.f;
; #pragma unroll
;         for (int i = 0; i < 16; ++i) { const float rp = G[(16 * sc + i) * 260 + c] + ba, ip = G[(16 * sc + i) * 260 + 128 + c] + bx;
;             const float rr = sigmoidf_(rp), ii = sigmoidf_(ip); const float a = fexp2(rr * nsp8);
;             const float mult = (sbase + i == 0) ? 1.0f : sqrtf(fmaxf(1.0f - a * a, 0.f));
;             const float u = mult * (ii * xbv[i]);
;             hl = a * hl + u; pp *= a; hloc[i] = hl; pv[i] = pp; }
	v_add_f32_e32 v6, v107, v12
	v_mul_f32_e32 v6, 0xbfb8aa3b, v6
	v_exp_f32_e32 v6, v6
	v_add_f32_e32 v8, v108, v13
	v_mul_f32_e32 v8, 0xbfb8aa3b, v8
	v_exp_f32_e32 v8, v8
	v_add_f32_e32 v6, 1.0, v6
	v_rcp_f32_e32 v6, v6
	v_add_f32_e32 v8, 1.0, v8
	v_rcp_f32_e32 v14, v8
	v_mul_f32_e32 v6, v109, v6
	v_exp_f32_e32 v15, v6
	s_nop 0
	v_fma_f32 v6, -v15, v15, 1.0
	v_max_f32_e32 v6, 0, v6
	v_cmp_gt_f32_e32 vcc, s79, v6
	v_mul_f32_e32 v8, 0x4f800000, v6
	s_nop 0
	v_cndmask_b32_e32 v6, v6, v8, vcc
	v_sqrt_f32_e32 v8, v6
	s_nop 0
	v_add_u32_e32 v10, -1, v8
	v_fma_f32 v12, -v10, v8, v6
	v_cmp_ge_f32_e64 s[16:17], 0, v12
	v_add_u32_e32 v12, 1, v8
	s_nop 0
	v_cndmask_b32_e64 v10, v8, v10, s[16:17]
	v_fma_f32 v8, -v12, v8, v6
	v_cmp_lt_f32_e64 s[16:17], 0, v8
	s_nop 1
	v_cndmask_b32_e64 v8, v10, v12, s[16:17]
	v_mul_f32_e32 v10, 0x37800000, v8
	v_cndmask_b32_e32 v8, v8, v10, vcc
	v_cmp_class_f32_e32 vcc, v6, v215
	v_pk_mul_f32 v[12:13], v[88:89], v[14:15]
	s_nop 0
	v_cndmask_b32_e32 v6, v8, v6, vcc
	v_fmac_f32_e32 v13, v12, v6
	v_mul_f32_e32 v6, v5, v15
	ds_read2st64_b32 v[14:15], v200 offset0:68 offset1:70
	v_mov_b32_e32 v87, v13
	s_waitcnt lgkmcnt(0)
	v_add_f32_e32 v8, v107, v14
	v_mul_f32_e32 v8, 0xbfb8aa3b, v8
	v_exp_f32_e32 v8, v8
	v_add_f32_e32 v10, v108, v15
	v_mul_f32_e32 v10, 0xbfb8aa3b, v10
	v_exp_f32_e32 v10, v10
	v_add_f32_e32 v8, 1.0, v8
	v_rcp_f32_e32 v8, v8
	v_add_f32_e32 v10, 1.0, v10
	v_rcp_f32_e32 v16, v10
	v_mul_f32_e32 v8, v109, v8
	v_exp_f32_e32 v17, v8
	s_nop 0
	v_fma_f32 v8, -v17, v17, 1.0
	v_max_f32_e32 v8, 0, v8
	v_cmp_gt_f32_e32 vcc, s79, v8
	v_mul_f32_e32 v10, 0x4f800000, v8
	s_nop 0
	v_cndmask_b32_e32 v8, v8, v10, vcc
	v_sqrt_f32_e32 v10, v8
	s_nop 0
	v_add_u32_e32 v12, -1, v10
	v_fma_f32 v14, -v12, v10, v8
	v_cmp_ge_f32_e64 s[16:17], 0, v14
	v_add_u32_e32 v14, 1, v10
	s_nop 0
	v_cndmask_b32_e64 v12, v10, v12, s[16:17]
	v_fma_f32 v10, -v14, v10, v8
	v_cmp_lt_f32_e64 s[16:17], 0, v10
	s_nop 1
	v_cndmask_b32_e64 v10, v12, v14, s[16:17]
	v_mul_f32_e32 v12, 0x37800000, v10
	v_cndmask_b32_e32 v10, v10, v12, vcc
	v_cmp_class_f32_e32 vcc, v8, v215
	v_pk_mul_f32 v[14:15], v[86:87], v[16:17]
	s_nop 0
	v_cndmask_b32_e32 v8, v10, v8, vcc
	v_fmac_f32_e32 v15, v14, v8
	v_mul_f32_e32 v8, v6, v17
	ds_read2st64_b32 v[16:17], v201 offset0:68 offset1:70
	v_mov_b32_e32 v85, v15
	s_waitcnt lgkmcnt(0)
	v_add_f32_e32 v10, v107, v16
	v_mul_f32_e32 v10, 0xbfb8aa3b, v10
	v_exp_f32_e32 v10, v10
	v_add_f32_e32 v12, v108, v17
	v_mul_f32_e32 v12, 0xbfb8aa3b, v12
	v_exp_f32_e32 v12, v12
	v_add_f32_e32 v10, 1.0, v10
	v_rcp_f32_e32 v10, v10
	v_add_f32_e32 v12, 1.0, v12
	v_rcp_f32_e32 v86, v12
	v_mul_f32_e32 v10, v109, v10
	v_exp_f32_e32 v87, v10
	s_nop 0
	v_fma_f32 v10, -v87, v87, 1.0
	v_max_f32_e32 v10, 0, v10
	v_cmp_gt_f32_e32 vcc, s79, v10
	v_mul_f32_e32 v12, 0x4f800000, v10
	s_nop 0
	v_cndmask_b32_e32 v10, v10, v12, vcc
	v_sqrt_f32_e32 v12, v10
	s_nop 0
	v_add_u32_e32 v14, -1, v12
	v_fma_f32 v16, -v14, v12, v10
	v_cmp_ge_f32_e64 s[16:17], 0, v16
	v_add_u32_e32 v16, 1, v12
	s_nop 0
	v_cndmask_b32_e64 v14, v12, v14, s[16:17]
	v_fma_f32 v12, -v16, v12, v10
	v_cmp_lt_f32_e64 s[16:17], 0, v12
	s_nop 1
	v_cndmask_b32_e64 v12, v14, v16, s[16:17]
	v_pk_mul_f32 v[16:17], v[84:85], v[86:87]
	ds_read2st64_b32 v[84:85], v202 offset0:68 offset1:70
	v_mul_f32_e32 v14, 0x37800000, v12
	v_cndmask_b32_e32 v12, v12, v14, vcc
	v_cmp_class_f32_e32 vcc, v10, v215
	s_waitcnt lgkmcnt(0)
	v_add_f32_e32 v14, v108, v85
	v_cndmask_b32_e32 v10, v12, v10, vcc
	v_add_f32_e32 v12, v107, v84
	v_mul_f32_e32 v12, 0xbfb8aa3b, v12
	v_exp_f32_e32 v12, v12
	v_mul_f32_e32 v14, 0xbfb8aa3b, v14
	v_exp_f32_e32 v14, v14
	v_fmac_f32_e32 v17, v16, v10
	v_add_f32_e32 v12, 1.0, v12
	v_rcp_f32_e32 v12, v12
	v_add_f32_e32 v14, 1.0, v14
	v_rcp_f32_e32 v84, v14
	v_mov_b32_e32 v79, v17
	v_mul_f32_e32 v12, v109, v12
	v_exp_f32_e32 v85, v12
	v_mul_f32_e32 v10, v8, v87
	v_fma_f32 v12, -v85, v85, 1.0
	v_max_f32_e32 v12, 0, v12
	v_cmp_gt_f32_e32 vcc, s79, v12
	v_mul_f32_e32 v14, 0x4f800000, v12
	v_pk_mul_f32 v[78:79], v[78:79], v[84:85]
	v_cndmask_b32_e32 v12, v12, v14, vcc
	v_sqrt_f32_e32 v14, v12
	s_nop 0
	v_add_u32_e32 v16, -1, v14
	v_fma_f32 v67, -v16, v14, v12
	v_cmp_ge_f32_e64 s[16:17], 0, v67
	v_add_u32_e32 v67, 1, v14
	s_nop 0
	v_cndmask_b32_e64 v16, v14, v16, s[16:17]
	v_fma_f32 v14, -v67, v14, v12
	v_cmp_lt_f32_e64 s[16:17], 0, v14
	s_nop 1
	v_cndmask_b32_e64 v14, v16, v67, s[16:17]
	v_mul_f32_e32 v16, 0x37800000, v14
	v_cndmask_b32_e32 v14, v14, v16, vcc
	v_cmp_class_f32_e32 vcc, v12, v215
	s_nop 1
	v_cndmask_b32_e32 v12, v14, v12, vcc
	v_fmac_f32_e32 v79, v78, v12
	v_mul_f32_e32 v12, v10, v85
	ds_read2st64_b32 v[84:85], v203 offset0:68 offset1:70
	v_mov_b32_e32 v83, v79
	s_waitcnt lgkmcnt(0)
	v_add_f32_e32 v14, v107, v84
	v_mul_f32_e32 v14, 0xbfb8aa3b, v14
	v_exp_f32_e32 v14, v14
	v_add_f32_e32 v16, v108, v85
	v_mul_f32_e32 v16, 0xbfb8aa3b, v16
	v_exp_f32_e32 v16, v16
	v_add_f32_e32 v14, 1.0, v14
	v_rcp_f32_e32 v14, v14
	v_add_f32_e32 v16, 1.0, v16
	v_rcp_f32_e32 v84, v16
	v_mul_f32_e32 v14, v109, v14
	v_exp_f32_e32 v85, v14
	s_nop 0
	v_fma_f32 v14, -v85, v85, 1.0
	v_max_f32_e32 v14, 0, v14
	v_cmp_gt_f32_e32 vcc, s79, v14
	v_mul_f32_e32 v16, 0x4f800000, v14
	v_pk_mul_f32 v[82:83], v[82:83], v[84:85]
	v_cndmask_b32_e32 v14, v14, v16, vcc
	v_sqrt_f32_e32 v16, v14
	s_nop 0
	v_add_u32_e32 v67, -1, v16
	v_fma_f32 v69, -v67, v16, v14
	v_cmp_ge_f32_e64 s[16:17], 0, v69
	v_add_u32_e32 v69, 1, v16
	s_nop 0
	v_cndmask_b32_e64 v67, v16, v67, s[16:17]
	v_fma_f32 v16, -v69, v16, v14
	v_cmp_lt_f32_e64 s[16:17], 0, v16
	s_nop 1
	v_cndmask_b32_e64 v16, v67, v69, s[16:17]
	v_mul_f32_e32 v67, 0x37800000, v16
	v_cndmask_b32_e32 v16, v16, v67, vcc
	v_cmp_class_f32_e32 vcc, v14, v215
	s_nop 1
	v_cndmask_b32_e32 v14, v16, v14, vcc
	v_fmac_f32_e32 v83, v82, v14
	v_mul_f32_e32 v14, v12, v85
	ds_read2st64_b32 v[84:85], v204 offset0:68 offset1:70
	v_mov_b32_e32 v81, v83
	s_waitcnt lgkmcnt(0)
; __device__ __forceinline__ float fexp2(float x) { return __builtin_amdgcn_exp2f(x); }
; __device__ __forceinline__ float sigmoidf_(float x) { return frcp(1.0f + fexp2(-x * LOG2E)); }
; __device__ __forceinline__ void lru_item(LAS unsigned char* lds, const Params& P, int l, int b, int g) {
;     ...
;         float hloc[16], pv[16]; float hl = 0.f, pp = 1.f;
; #pragma unroll
;         for (int i = 0; i < 16; ++i) { const float rp = G[(16 * sc + i) * 260 + c] + ba, ip = G[(16 * sc + i) * 260 + 128 + c] + bx;
;             const float rr = sigmoidf_(rp), ii = sigmoidf_(ip); const float a = fexp2(rr * nsp8);
;             const float mult = (sbase + i == 0) ? 1.0f : sqrtf(fmaxf(1.0f - a * a, 0.f));
;             const float u = mult * (ii * xbv[i]);
;             hl = a * hl + u; pp *= a; hloc[i] = hl; pv[i] = pp; }
	v_add_f32_e32 v16, v107, v84
	v_mul_f32_e32 v16, 0xbfb8aa3b, v16
	v_exp_f32_e32 v16, v16
	v_add_f32_e32 v67, v108, v85
	v_mul_f32_e32 v67, 0xbfb8aa3b, v67
	v_exp_f32_e32 v67, v67
	v_add_f32_e32 v16, 1.0, v16
	v_rcp_f32_e32 v16, v16
	v_add_f32_e32 v67, 1.0, v67
	v_rcp_f32_e32 v84, v67
	v_mul_f32_e32 v16, v109, v16
	v_exp_f32_e32 v85, v16
	s_nop 0
	v_fma_f32 v16, -v85, v85, 1.0
	v_max_f32_e32 v16, 0, v16
	v_cmp_gt_f32_e32 vcc, s79, v16
	v_mul_f32_e32 v67, 0x4f800000, v16
	v_pk_mul_f32 v[80:81], v[80:81], v[84:85]
	v_cndmask_b32_e32 v16, v16, v67, vcc
	v_sqrt_f32_e32 v67, v16
	s_nop 0
	v_add_u32_e32 v69, -1, v67
	v_fma_f32 v71, -v69, v67, v16
	v_cmp_ge_f32_e64 s[16:17], 0, v71
	v_add_u32_e32 v71, 1, v67
	s_nop 0
	v_cndmask_b32_e64 v69, v67, v69, s[16:17]
	v_fma_f32 v67, -v71, v67, v16
	v_cmp_lt_f32_e64 s[16:17], 0, v67
	s_nop 1
	v_cndmask_b32_e64 v67, v69, v71, s[16:17]
	v_mul_f32_e32 v69, 0x37800000, v67
	v_cndmask_b32_e32 v67, v67, v69, vcc
	v_cmp_class_f32_e32 vcc, v16, v215
	s_nop 1
	v_cndmask_b32_e32 v16, v67, v16, vcc
	v_fmac_f32_e32 v81, v80, v16
	v_mul_f32_e32 v16, v14, v85
	ds_read2st64_b32 v[84:85], v205 offset0:68 offset1:70
	v_mov_b32_e32 v77, v81
	s_waitcnt lgkmcnt(0)
	v_add_f32_e32 v67, v107, v84
	v_mul_f32_e32 v67, 0xbfb8aa3b, v67
	v_exp_f32_e32 v67, v67
	v_add_f32_e32 v69, v108, v85
	v_mul_f32_e32 v69, 0xbfb8aa3b, v69
	v_exp_f32_e32 v69, v69
	v_add_f32_e32 v67, 1.0, v67
	v_rcp_f32_e32 v67, v67
	v_add_f32_e32 v69, 1.0, v69
	v_rcp_f32_e32 v84, v69
	v_mul_f32_e32 v67, v109, v67
	v_exp_f32_e32 v85, v67
	s_nop 0
	v_fma_f32 v67, -v85, v85, 1.0
	v_max_f32_e32 v67, 0, v67
	v_cmp_gt_f32_e32 vcc, s79, v67
	v_mul_f32_e32 v69, 0x4f800000, v67
	v_pk_mul_f32 v[76:77], v[76:77], v[84:85]
	v_cndmask_b32_e32 v67, v67, v69, vcc
	v_sqrt_f32_e32 v69, v67
	s_nop 0
	v_add_u32_e32 v71, -1, v69
	v_fma_f32 v73, -v71, v69, v67
	v_cmp_ge_f32_e64 s[16:17], 0, v73
	v_add_u32_e32 v73, 1, v69
	s_nop 0
	v_cndmask_b32_e64 v71, v69, v71, s[16:17]
	v_fma_f32 v69, -v73, v69, v67
	v_cmp_lt_f32_e64 s[16:17], 0, v69
	s_nop 1
	v_cndmask_b32_e64 v69, v71, v73, s[16:17]
	v_mul_f32_e32 v71, 0x37800000, v69
	v_cndmask_b32_e32 v69, v69, v71, vcc
	v_cmp_class_f32_e32 vcc, v67, v215
	s_nop 1
	v_cndmask_b32_e32 v67, v69, v67, vcc
	v_fmac_f32_e32 v77, v76, v67
	v_mul_f32_e32 v76, v16, v85
	ds_read2st64_b32 v[84:85], v206 offset0:68 offset1:70
	v_mov_b32_e32 v75, v77
	s_waitcnt lgkmcnt(0)
	v_add_f32_e32 v67, v107, v84
	v_mul_f32_e32 v67, 0xbfb8aa3b, v67
	v_exp_f32_e32 v67, v67
	v_add_f32_e32 v69, v108, v85
	v_mul_f32_e32 v69, 0xbfb8aa3b, v69
	v_exp_f32_e32 v69, v69
	v_add_f32_e32 v67, 1.0, v67
	v_rcp_f32_e32 v67, v67
	v_add_f32_e32 v69, 1.0, v69
	v_rcp_f32_e32 v84, v69
	v_mul_f32_e32 v67, v109, v67
	v_exp_f32_e32 v85, v67
	s_nop 0
	v_fma_f32 v67, -v85, v85, 1.0
	v_max_f32_e32 v67, 0, v67
	v_cmp_gt_f32_e32 vcc, s79, v67
	v_mul_f32_e32 v69, 0x4f800000, v67
	v_pk_mul_f32 v[74:75], v[74:75], v[84:85]
	v_cndmask_b32_e32 v67, v67, v69, vcc
	v_sqrt_f32_e32 v69, v67
	s_nop 0
	v_add_u32_e32 v71, -1, v69
	v_fma_f32 v73, -v71, v69, v67
	v_cmp_ge_f32_e64 s[16:17], 0, v73
	v_add_u32_e32 v73, 1, v69
	s_nop 0
	v_cndmask_b32_e64 v71, v69, v71, s[16:17]
	v_fma_f32 v69, -v73, v69, v67
	v_cmp_lt_f32_e64 s[16:17], 0, v69
	s_nop 1
	v_cndmask_b32_e64 v69, v71, v73, s[16:17]
	v_mul_f32_e32 v71, 0x37800000, v69
	v_cndmask_b32_e32 v69, v69, v71, vcc
	v_cmp_class_f32_e32 vcc, v67, v215
	s_nop 1
	v_cndmask_b32_e32 v67, v69, v67, vcc
	v_fmac_f32_e32 v75, v74, v67
	v_mul_f32_e32 v74, v76, v85
	ds_read2st64_b32 v[84:85], v207 offset0:68 offset1:70
	s_waitcnt lgkmcnt(0)
	v_add_f32_e32 v67, v107, v84
	v_mul_f32_e32 v67, 0xbfb8aa3b, v67
	v_exp_f32_e32 v67, v67
	v_add_f32_e32 v69, v108, v85
	v_mul_f32_e32 v69, 0xbfb8aa3b, v69
	v_exp_f32_e32 v69, v69
	v_add_f32_e32 v67, 1.0, v67
	v_rcp_f32_e32 v67, v67
	v_add_f32_e32 v69, 1.0, v69
	v_rcp_f32_e32 v84, v69
	v_mul_f32_e32 v67, v109, v67
	v_exp_f32_e32 v85, v67
	s_nop 0
	v_fma_f32 v67, -v85, v85, 1.0
	v_max_f32_e32 v67, 0, v67
	v_cmp_gt_f32_e32 vcc, s79, v67
	v_mul_f32_e32 v69, 0x4f800000, v67
	s_nop 0
	v_cndmask_b32_e32 v67, v67, v69, vcc
	v_sqrt_f32_e32 v69, v67
	s_nop 0
	v_add_u32_e32 v71, -1, v69
	v_fma_f32 v73, -v71, v69, v67
	v_cmp_ge_f32_e64 s[16:17], 0, v73
	v_add_u32_e32 v73, 1, v69
	s_nop 0
	v_cndmask_b32_e64 v71, v69, v71, s[16:17]
	v_fma_f32 v69, -v73, v69, v67
	v_cmp_lt_f32_e64 s[16:17], 0, v69
	s_nop 1
	v_cndmask_b32_e64 v69, v71, v73, s[16:17]
	v_mul_f32_e32 v71, 0x37800000, v69
	v_cndmask_b32_e32 v69, v69, v71, vcc
	v_cmp_class_f32_e32 vcc, v67, v215
	v_mov_b32_e32 v73, v75
	v_pk_mul_f32 v[72:73], v[72:73], v[84:85]
	v_cndmask_b32_e32 v67, v69, v67, vcc
	v_fmac_f32_e32 v73, v72, v67
	v_mul_f32_e32 v72, v74, v85
	ds_read2st64_b32 v[84:85], v208 offset0:68 offset1:70
	s_waitcnt lgkmcnt(0)
; __device__ __forceinline__ float fexp2(float x) { return __builtin_amdgcn_exp2f(x); }
; __device__ __forceinline__ float sigmoidf_(float x) { return frcp(1.0f + fexp2(-x * LOG2E)); }
; __device__ __forceinline__ void lru_item(LAS unsigned char* lds, const Params& P, int l, int b, int g) {
;     ...
;         for (int i = 0; i < 16; ++i) { const float rp = G[(16 * sc + i) * 260 + c] + ba, ip = G[(16 * sc + i) * 260 + 128 + c] + bx;
;             const float rr = sigmoidf_(rp), ii = sigmoidf_(ip); const float a = fexp2(rr * nsp8);
;             const float mult = (sbase + i == 0) ? 1.0f : sqrtf(fmaxf(1.0f - a * a, 0.f));
;             const float u = mult * (ii * xbv[i]);
;             hl = a * hl + u; pp *= a; hloc[i] = hl; pv[i] = pp; }
;         comp[sc * 128 + c] = (f32x2){pp, hl};
;         __syncthreads();
;         float cin = carry[(ch & 1) * 128 + c];
; #pragma unroll
;         for (int j = 0; j < 3; ++j) if (j < sc) { const f32x2 cj = comp[j * 128 + c]; cin = cj.x * cin + cj.y; }
;         if (sc == 3) carry[((ch + 1) & 1) * 128 + c] = pp * cin + hl;
	v_add_f32_e32 v67, v107, v84
	v_mul_f32_e32 v67, 0xbfb8aa3b, v67
	v_exp_f32_e32 v67, v67
	v_add_f32_e32 v69, v108, v85
	v_mul_f32_e32 v69, 0xbfb8aa3b, v69
	v_exp_f32_e32 v69, v69
	v_add_f32_e32 v67, 1.0, v67
	v_rcp_f32_e32 v67, v67
	v_add_f32_e32 v69, 1.0, v69
	v_rcp_f32_e32 v84, v69
	v_mul_f32_e32 v67, v109, v67
	v_exp_f32_e32 v85, v67
	s_nop 0
	v_fma_f32 v67, -v85, v85, 1.0
	v_max_f32_e32 v67, 0, v67
	v_cmp_gt_f32_e32 vcc, s79, v67
	v_mul_f32_e32 v69, 0x4f800000, v67
	s_nop 0
	v_cndmask_b32_e32 v67, v67, v69, vcc
	v_sqrt_f32_e32 v69, v67
	s_nop 0
	v_add_u32_e32 v71, -1, v69
	v_fma_f32 v78, -v71, v69, v67
	v_cmp_ge_f32_e64 s[16:17], 0, v78
	v_add_u32_e32 v78, 1, v69
	s_nop 0
	v_cndmask_b32_e64 v71, v69, v71, s[16:17]
	v_fma_f32 v69, -v78, v69, v67
	v_cmp_lt_f32_e64 s[16:17], 0, v69
	s_nop 1
	v_cndmask_b32_e64 v69, v71, v78, s[16:17]
	v_mul_f32_e32 v71, 0x37800000, v69
	v_cndmask_b32_e32 v69, v69, v71, vcc
	v_cmp_class_f32_e32 vcc, v67, v215
	v_mov_b32_e32 v71, v73
	v_pk_mul_f32 v[70:71], v[70:71], v[84:85]
	v_cndmask_b32_e32 v67, v69, v67, vcc
	v_fmac_f32_e32 v71, v70, v67
	v_mul_f32_e32 v70, v72, v85
	ds_read2st64_b32 v[84:85], v209 offset0:68 offset1:70
	s_waitcnt lgkmcnt(0)
	v_add_f32_e32 v67, v107, v84
	v_mul_f32_e32 v67, 0xbfb8aa3b, v67
	v_exp_f32_e32 v67, v67
	v_add_f32_e32 v69, v108, v85
	v_mul_f32_e32 v69, 0xbfb8aa3b, v69
	v_exp_f32_e32 v69, v69
	v_add_f32_e32 v67, 1.0, v67
	v_rcp_f32_e32 v67, v67
	v_add_f32_e32 v69, 1.0, v69
	v_rcp_f32_e32 v84, v69
	v_mul_f32_e32 v67, v109, v67
	v_exp_f32_e32 v85, v67
	s_nop 0
	v_fma_f32 v67, -v85, v85, 1.0
	v_max_f32_e32 v67, 0, v67
	v_cmp_gt_f32_e32 vcc, s79, v67
	v_mul_f32_e32 v69, 0x4f800000, v67
	s_nop 0
	v_cndmask_b32_e32 v67, v67, v69, vcc
	v_sqrt_f32_e32 v69, v67
	s_nop 0
	v_add_u32_e32 v78, -1, v69
	v_fma_f32 v80, -v78, v69, v67
	v_cmp_ge_f32_e64 s[16:17], 0, v80
	v_add_u32_e32 v80, 1, v69
	s_nop 0
	v_cndmask_b32_e64 v78, v69, v78, s[16:17]
	v_fma_f32 v69, -v80, v69, v67
	v_cmp_lt_f32_e64 s[16:17], 0, v69
	s_nop 1
	v_cndmask_b32_e64 v69, v78, v80, s[16:17]
	v_mul_f32_e32 v78, 0x37800000, v69
	v_cndmask_b32_e32 v69, v69, v78, vcc
	v_cmp_class_f32_e32 vcc, v67, v215
	s_nop 1
	v_cndmask_b32_e32 v67, v69, v67, vcc
	v_mov_b32_e32 v69, v71
	v_pk_mul_f32 v[68:69], v[68:69], v[84:85]
	s_nop 0
	v_fmac_f32_e32 v69, v68, v67
	v_mul_f32_e32 v68, v70, v85
	ds_read2st64_b32 v[84:85], v210 offset0:68 offset1:70
	s_waitcnt lgkmcnt(0)
	v_add_f32_e32 v67, v107, v84
	v_mul_f32_e32 v67, 0xbfb8aa3b, v67
	v_exp_f32_e32 v67, v67
	v_add_f32_e32 v78, v108, v85
	v_mul_f32_e32 v78, 0xbfb8aa3b, v78
	v_exp_f32_e32 v78, v78
	v_add_f32_e32 v67, 1.0, v67
	v_rcp_f32_e32 v67, v67
	v_add_f32_e32 v78, 1.0, v78
	v_rcp_f32_e32 v84, v78
	v_mul_f32_e32 v67, v109, v67
	v_exp_f32_e32 v85, v67
	s_nop 0
	v_fma_f32 v67, -v85, v85, 1.0
	v_max_f32_e32 v67, 0, v67
	v_cmp_gt_f32_e32 vcc, s79, v67
	v_mul_f32_e32 v78, 0x4f800000, v67
	s_nop 0
	v_cndmask_b32_e32 v67, v67, v78, vcc
	v_sqrt_f32_e32 v78, v67
	s_nop 0
	v_add_u32_e32 v80, -1, v78
	v_fma_f32 v82, -v80, v78, v67
	v_cmp_ge_f32_e64 s[16:17], 0, v82
	v_add_u32_e32 v82, 1, v78
	s_nop 0
	v_cndmask_b32_e64 v80, v78, v80, s[16:17]
	v_fma_f32 v78, -v82, v78, v67
	v_cmp_lt_f32_e64 s[16:17], 0, v78
	s_nop 1
	v_cndmask_b32_e64 v78, v80, v82, s[16:17]
	v_mul_f32_e32 v80, 0x37800000, v78
	v_cndmask_b32_e32 v78, v78, v80, vcc
	v_cmp_class_f32_e32 vcc, v67, v215
	s_nop 1
	v_cndmask_b32_e32 v78, v78, v67, vcc
	v_mov_b32_e32 v67, v69
	v_pk_mul_f32 v[66:67], v[66:67], v[84:85]
	s_nop 0
	v_fmac_f32_e32 v67, v66, v78
	v_mul_f32_e32 v66, v68, v85
	v_lshl_add_u32 v78, s1, 2, v192
	ds_write_b64 v191, v[66:67]
	s_waitcnt lgkmcnt(0)
	s_waitcnt vmcnt(0)
	s_barrier
	ds_read_b32 v78, v78
	s_and_saveexec_b64 s[16:17], s[8:9]
	s_cbranch_execnz .LBB0_262
	s_or_b64 exec, exec, s[16:17]
	s_and_saveexec_b64 s[16:17], s[12:13]
	s_cbranch_execnz .LBB0_263

; __device__ __forceinline__ void lru_item(LAS unsigned char* lds, const Params& P, int l, int b, int g) {
;     ...
;         for (int i = 0; i < 19; ++i) { const int s = sbase - 3 + i; xrv[i] = (s >= 0) ? bf2f(XR[(rowb + (s >= 0 ? s : 0)) * DM + c0 + c]) : 0.f; }
;     ...
;         float cin = carry[(ch & 1) * 128 + c];
; #pragma unroll
;         for (int j = 0; j < 3; ++j) if (j < sc) { const f32x2 cj = comp[j * 128 + c]; cin = cj.x * cin + cj.y; }
;         if (sc == 3) carry[((ch + 1) & 1) * 128 + c] = pp * cin + hl;
.LBB0_256:
	s_or_b64 exec, exec, s[16:17]
	s_waitcnt lgkmcnt(0)
	v_fma_f32 v80, v66, v78, v67
	s_and_saveexec_b64 s[16:17], s[10:11]
	s_xor_b64 s[16:17], exec, s[16:17]
	v_fmac_f32_e32 v67, v66, v78
	s_andn2_saveexec_b64 s[16:17], s[16:17]
	s_cbranch_execz .LBB0_247
	v_bitop3_b32 v66, s1, v224, v186 bitop3:0x36
	v_lshl_add_u32 v66, v66, 2, 0
	v_add_u32_e32 v66, 0x15800, v66
	v_mov_b32_e32 v67, v80
	ds_write_b32 v66, v80
	s_branch .LBB0_247
.LBB0_262:
	ds_read_b64 v[84:85], v193
	s_waitcnt lgkmcnt(0)
	v_fmac_f32_e32 v85, v78, v84
	v_mov_b32_e32 v78, v85
	s_or_b64 exec, exec, s[16:17]
	s_and_saveexec_b64 s[16:17], s[12:13]
	s_cbranch_execz .LBB0_254

.LBB0_1284:
	v_add_u32_e32 v1, s73, v229
	v_cvt_f32_i32_e32 v1, v1
	s_bitcmp1_b32 s74, 0
	s_cselect_b32 s20, 0x4800, 0
	v_mov_b32_e32 v173, v172
	v_fma_f32 v12, v172, v1, -v230
	v_add_u32_e32 v1, s20, v169
	ds_read_b128 v[4:7], v1
	ds_read_b128 v[8:11], v1 offset:32
	ds_read_b128 v[232:235], v1 offset:64
	ds_read_b128 v[236:239], v1 offset:96
	v_fma_f32 v80, 0, v172, v12
	v_add_f32_e32 v81, v172, v12
	v_pk_fma_f32 v[82:83], v[180:181], s[28:29], v[12:13] op_sel_hi:[1,1,0]
	v_pk_fma_f32 v[84:85], v[180:181], s[30:31], v[12:13] op_sel_hi:[1,1,0]
	v_pk_fma_f32 v[86:87], v[180:181], s[34:35], v[12:13] op_sel_hi:[1,1,0]
	v_pk_fma_f32 v[88:89], v[180:181], s[36:37], v[12:13] op_sel_hi:[1,1,0]
	v_pk_fma_f32 v[90:91], v[180:181], s[38:39], v[12:13] op_sel_hi:[1,1,0]
	v_pk_fma_f32 v[92:93], v[180:181], s[40:41], v[12:13] op_sel_hi:[1,1,0]
	v_pk_fma_f32 v[94:95], v[180:181], s[42:43], v[12:13] op_sel_hi:[1,1,0]
	v_pk_fma_f32 v[110:111], v[172:173], s[44:45], v[12:13] op_sel_hi:[1,1,0]
	v_pk_fma_f32 v[108:109], v[172:173], s[46:47], v[12:13] op_sel_hi:[1,1,0]
	s_waitcnt lgkmcnt(3)
	v_mfma_f32_32x32x16_bf16 v[80:95], v[4:7], v[112:115], v[80:95]
	ds_read_b128 v[4:7], v1 offset:4608
	v_fma_f32 v106, v172, s48, v12
	v_fma_f32 v107, v173, s49, v12
	v_fma_f32 v104, v172, s50, v12
	v_fma_f32 v105, v173, s51, v12
	v_pk_fma_f32 v[102:103], v[172:173], s[52:53], v[12:13] op_sel_hi:[1,1,0]
	v_pk_fma_f32 v[100:101], v[172:173], s[54:55], v[12:13] op_sel_hi:[1,1,0]
	v_pk_fma_f32 v[98:99], v[172:173], s[56:57], v[12:13] op_sel_hi:[1,1,0]
	v_pk_fma_f32 v[96:97], v[182:183], s[58:59], v[12:13] op_sel_hi:[1,1,0]
	s_waitcnt lgkmcnt(3)
	v_mfma_f32_32x32x16_bf16 v[80:95], v[8:11], v[116:119], v[80:95]
	ds_read_b128 v[8:11], v1 offset:4640
	s_addk_i32 s17, 0x7f
	s_cmp_le_i32 s17, s70
	s_waitcnt lgkmcnt(3)
	v_mfma_f32_32x32x16_bf16 v[80:95], v[232:235], v[120:123], v[80:95]
	ds_read_b128 v[232:235], v1 offset:4672
	s_waitcnt lgkmcnt(3)
	v_mfma_f32_32x32x16_bf16 v[80:95], v[236:239], v[124:127], v[80:95]
	ds_read_b128 v[236:239], v1 offset:4704
	s_waitcnt lgkmcnt(3)
	v_mfma_f32_32x32x16_bf16 v[96:111], v[4:7], v[112:115], v[96:111]
	s_waitcnt lgkmcnt(2)
	v_mfma_f32_32x32x16_bf16 v[96:111], v[8:11], v[116:119], v[96:111]
	s_waitcnt lgkmcnt(1)
	v_mfma_f32_32x32x16_bf16 v[96:111], v[232:235], v[120:123], v[96:111]
	s_waitcnt lgkmcnt(0)
	v_mfma_f32_32x32x16_bf16 v[96:111], v[236:239], v[124:127], v[96:111]
	s_cbranch_scc1 .LBB0_1286
	v_cmp_lt_i32_e32 vcc, -1, v228
	s_nop 1
	v_cndmask_b32_e32 v80, v224, v80, vcc
	v_cmp_lt_i32_e32 vcc, 0, v228
	s_nop 1
	v_cndmask_b32_e32 v81, v224, v81, vcc
	v_cmp_lt_i32_e32 vcc, 1, v228
	s_nop 1
	v_cndmask_b32_e32 v82, v224, v82, vcc
	v_cmp_lt_i32_e32 vcc, 2, v228
	s_nop 1
	v_cndmask_b32_e32 v83, v224, v83, vcc
	v_cmp_lt_i32_e32 vcc, 3, v228
	s_nop 1
	v_cndmask_b32_e32 v84, v224, v84, vcc
	v_cmp_lt_i32_e32 vcc, 4, v228
	s_nop 1
	v_cndmask_b32_e32 v85, v224, v85, vcc
	v_cmp_lt_i32_e32 vcc, 5, v228
	s_nop 1
	v_cndmask_b32_e32 v86, v224, v86, vcc
	v_cmp_lt_i32_e32 vcc, 6, v228
	s_nop 1
	v_cndmask_b32_e32 v87, v224, v87, vcc
	v_cmp_lt_i32_e32 vcc, 15, v228
	s_nop 1
	v_cndmask_b32_e32 v88, v224, v88, vcc
	v_cmp_lt_i32_e32 vcc, 16, v228
	s_nop 1
	v_cndmask_b32_e32 v89, v224, v89, vcc
	v_cmp_lt_i32_e32 vcc, 17, v228
	s_nop 1
	v_cndmask_b32_e32 v90, v224, v90, vcc
	v_cmp_lt_i32_e32 vcc, 18, v228
	s_nop 1
	v_cndmask_b32_e32 v91, v224, v91, vcc
	v_cmp_lt_i32_e32 vcc, 19, v228
	s_nop 1
	v_cndmask_b32_e32 v92, v224, v92, vcc
	v_cmp_lt_i32_e32 vcc, 20, v228
	s_nop 1
	v_cndmask_b32_e32 v93, v224, v93, vcc
	v_cmp_lt_i32_e32 vcc, 21, v228
	s_nop 1
	v_cndmask_b32_e32 v94, v224, v94, vcc
	v_cmp_lt_i32_e32 vcc, 22, v228
	s_nop 1
	v_cndmask_b32_e32 v95, v224, v95, vcc
	v_cmp_lt_i32_e32 vcc, 31, v228
	s_nop 1
	v_cndmask_b32_e32 v96, v224, v96, vcc
	v_cmp_lt_i32_e32 vcc, 32, v228
	s_nop 1
	v_cndmask_b32_e32 v97, v224, v97, vcc
	v_cmp_lt_i32_e32 vcc, 33, v228
	s_nop 1
	v_cndmask_b32_e32 v98, v224, v98, vcc
	v_cmp_lt_i32_e32 vcc, 34, v228
	s_nop 1
	v_cndmask_b32_e32 v99, v224, v99, vcc
	v_cmp_lt_i32_e32 vcc, 35, v228
	s_nop 1
	v_cndmask_b32_e32 v100, v224, v100, vcc
	v_cmp_lt_i32_e32 vcc, 36, v228
	s_nop 1
	v_cndmask_b32_e32 v101, v224, v101, vcc
	v_cmp_lt_i32_e32 vcc, 37, v228
	s_nop 1
	v_cndmask_b32_e32 v102, v224, v102, vcc
	v_cmp_lt_i32_e32 vcc, 38, v228
	s_nop 1
	v_cndmask_b32_e32 v103, v224, v103, vcc
	v_cmp_lt_i32_e32 vcc, 47, v228
	s_nop 1
	v_cndmask_b32_e32 v104, v224, v104, vcc
	v_cmp_lt_i32_e32 vcc, 48, v228
	s_nop 1
	v_cndmask_b32_e32 v105, v224, v105, vcc
	v_cmp_lt_i32_e32 vcc, 49, v228
	s_nop 1
	v_cndmask_b32_e32 v106, v224, v106, vcc
	v_cmp_lt_i32_e32 vcc, 50, v228
	s_nop 1
	v_cndmask_b32_e32 v107, v224, v107, vcc
	v_cmp_lt_i32_e32 vcc, 51, v228
	s_nop 1
	v_cndmask_b32_e32 v108, v224, v108, vcc
	v_cmp_lt_i32_e32 vcc, 52, v228
	s_nop 1
	v_cndmask_b32_e32 v109, v224, v109, vcc
	v_cmp_lt_i32_e32 vcc, 53, v228
	s_nop 1
	v_cndmask_b32_e32 v110, v224, v110, vcc
	v_cmp_lt_i32_e32 vcc, 54, v228
	s_nop 1
	v_cndmask_b32_e32 v111, v224, v111, vcc

.LBB0_1293:
	v_exp_f32_e32 v173, v80
	v_exp_f32_e32 v231, v81
	v_exp_f32_e32 v232, v82
	v_exp_f32_e32 v233, v83
	v_exp_f32_e32 v234, v84
	v_exp_f32_e32 v235, v85
	v_exp_f32_e32 v236, v86
	v_exp_f32_e32 v237, v87
	v_exp_f32_e32 v238, v88
	v_exp_f32_e32 v239, v89
	v_exp_f32_e32 v241, v90
	v_exp_f32_e32 v242, v91
	v_exp_f32_e32 v243, v92
	v_exp_f32_e32 v244, v93
	v_exp_f32_e32 v245, v94
	v_exp_f32_e32 v246, v95
	v_exp_f32_e32 v1, v96
	v_exp_f32_e32 v3, v97
	v_exp_f32_e32 v4, v98
	v_exp_f32_e32 v5, v99
	v_exp_f32_e32 v6, v100
	v_exp_f32_e32 v7, v101
	v_exp_f32_e32 v8, v102
	v_exp_f32_e32 v9, v103
	v_exp_f32_e32 v10, v104
	v_exp_f32_e32 v11, v105
	v_exp_f32_e32 v12, v106
	v_exp_f32_e32 v13, v107
	v_exp_f32_e32 v14, v108
	v_exp_f32_e32 v15, v109
	v_exp_f32_e32 v96, v110
	v_exp_f32_e32 v97, v111
	v_cvt_pk_bf16_f32 v80, v173, v231
	v_cvt_pk_bf16_f32 v81, v232, v233
	v_cvt_pk_bf16_f32 v82, v234, v235
	v_cvt_pk_bf16_f32 v83, v236, v237
	v_cvt_pk_bf16_f32 v88, v238, v239
	v_cvt_pk_bf16_f32 v89, v241, v242
	v_cvt_pk_bf16_f32 v90, v243, v244
	v_cvt_pk_bf16_f32 v91, v245, v246
	v_cvt_pk_bf16_f32 v84, v1, v3
	v_cvt_pk_bf16_f32 v85, v4, v5
	v_cvt_pk_bf16_f32 v86, v6, v7
	v_cvt_pk_bf16_f32 v87, v8, v9
	v_cvt_pk_bf16_f32 v92, v10, v11
	v_cvt_pk_bf16_f32 v93, v12, v13
	v_cvt_pk_bf16_f32 v94, v14, v15
	v_cvt_pk_bf16_f32 v95, v96, v97
	s_andn2_b64 vcc, exec, s[60:61]
	s_mov_b64 s[66:67], -1
	s_cbranch_vccnz .LBB0_1295
	s_mul_hi_i32 s17, s74, 0x55555556
	s_lshr_b32 s20, s17, 31
	s_add_i32 s17, s17, s20
	s_mul_i32 s17, s17, 3
	s_sub_i32 s17, s74, s17
	s_mulk_i32 s17, 0x4800
	v_add_u32_e32 v102, s17, v184
	ds_read_b128 v[98:101], v102 offset:36864
	ds_read_b128 v[104:107], v102 offset:41472
	ds_read_b128 v[108:111], v102 offset:36896
	s_mov_b64 s[66:67], 0
	s_waitcnt lgkmcnt(2)
	v_mfma_f32_32x32x16_bf16 v[64:79], v[98:101], v[80:83], v[64:79]
	ds_read_b128 v[98:101], v102 offset:36928
	s_waitcnt lgkmcnt(2)
	v_mfma_f32_32x32x16_bf16 v[48:63], v[104:107], v[80:83], v[48:63]
	ds_read_b128 v[104:107], v102 offset:36960
	s_waitcnt lgkmcnt(2)
	v_mfma_f32_32x32x16_bf16 v[64:79], v[108:111], v[88:91], v[64:79]
	ds_read_b128 v[108:111], v102 offset:41504
	s_waitcnt lgkmcnt(2)
	v_mfma_f32_32x32x16_bf16 v[64:79], v[98:101], v[84:87], v[64:79]
	ds_read_b128 v[98:101], v102 offset:41536
	s_waitcnt lgkmcnt(2)
	v_mfma_f32_32x32x16_bf16 v[64:79], v[104:107], v[92:95], v[64:79]
	ds_read_b128 v[104:107], v102 offset:41568
	s_waitcnt lgkmcnt(2)
	v_mfma_f32_32x32x16_bf16 v[48:63], v[108:111], v[88:91], v[48:63]
	ds_read_b128 v[108:111], v102 offset:46080
	s_waitcnt lgkmcnt(2)
	v_mfma_f32_32x32x16_bf16 v[48:63], v[98:101], v[84:87], v[48:63]
	ds_read_b128 v[98:101], v102 offset:46112
	s_waitcnt lgkmcnt(2)
	v_mfma_f32_32x32x16_bf16 v[48:63], v[104:107], v[92:95], v[48:63]
	ds_read_b128 v[104:107], v102 offset:46144
	s_waitcnt lgkmcnt(2)
	v_mfma_f32_32x32x16_bf16 v[32:47], v[108:111], v[80:83], v[32:47]
	ds_read_b128 v[108:111], v102 offset:46176
	s_waitcnt lgkmcnt(2)
	v_mfma_f32_32x32x16_bf16 v[32:47], v[98:101], v[88:91], v[32:47]
	ds_read_b128 v[98:101], v102 offset:50688
	s_waitcnt lgkmcnt(2)
	v_mfma_f32_32x32x16_bf16 v[32:47], v[104:107], v[84:87], v[32:47]
	ds_read_b128 v[104:107], v102 offset:50720
	s_waitcnt lgkmcnt(2)
	v_mfma_f32_32x32x16_bf16 v[32:47], v[108:111], v[92:95], v[32:47]
	ds_read_b128 v[108:111], v102 offset:50752
	s_waitcnt lgkmcnt(2)
	v_mfma_f32_32x32x16_bf16 v[16:31], v[98:101], v[80:83], v[16:31]
	ds_read_b128 v[98:101], v102 offset:50784
	s_waitcnt lgkmcnt(2)
	v_mfma_f32_32x32x16_bf16 v[16:31], v[104:107], v[88:91], v[16:31]
	s_waitcnt lgkmcnt(1)
	v_mfma_f32_32x32x16_bf16 v[16:31], v[108:111], v[84:87], v[16:31]
	s_waitcnt lgkmcnt(0)
	v_mfma_f32_32x32x16_bf16 v[16:31], v[98:101], v[92:95], v[16:31]

.LBB0_1309:
	s_and_b64 vcc, exec, s[16:17]
	s_cbranch_vccz .LBB0_1268
	v_readfirstlane_b32 s0, v160
	s_ashr_i32 s19, s18, 31
	s_lshr_b32 s0, s0, 1
	s_lshl_b64 s[16:17], s[18:19], 8
	s_and_b32 s1, s0, 0x7fffffe0
	s_add_u32 s0, s16, s1
	s_addc_u32 s16, s17, 0
	s_add_u32 s0, s0, 0x800
	s_addc_u32 s16, s16, 0
	v_mov_b32_e32 v3, s16
	v_or_b32_e32 v2, s0, v146
	v_lshlrev_b64 v[2:3], 8, v[2:3]
	v_lshl_add_u64 v[2:3], v[154:155], 0, v[2:3]
	s_lshl_b32 s16, s18, 7
	v_readlane_b32 s60, v252, 0
	global_load_dwordx4 v[18:21], v[2:3], off
	global_load_dwordx4 v[22:25], v[2:3], off offset:32
	global_load_dwordx4 v[26:29], v[2:3], off offset:64
	global_load_dwordx4 v[30:33], v[2:3], off offset:96
	global_load_dwordx4 v[34:37], v[2:3], off offset:128
	global_load_dwordx4 v[38:41], v[2:3], off offset:160
	global_load_dwordx4 v[42:45], v[2:3], off offset:192
	global_load_dwordx4 v[46:49], v[2:3], off offset:224
	v_add_u32_e32 v2, s16, v187
	v_add_u32_e32 v4, s16, v188
	v_readlane_b32 s61, v252, 1
	v_readlane_b32 s62, v252, 2
	v_readlane_b32 s63, v252, 3
	v_readlane_b32 s68, v252, 8
	v_readlane_b32 s69, v252, 9
	v_ashrrev_i32_e32 v5, 31, v4
	v_readlane_b32 s70, v252, 10
	v_readlane_b32 s71, v252, 11
	s_mov_b64 s[60:61], s[68:69]
	v_add_u32_e32 v6, s16, v189
	v_add_u32_e32 v8, s16, v190
	v_add_u32_e32 v10, s16, v191
	v_ashrrev_i32_e32 v3, 31, v2
	v_readlane_b32 s66, v252, 6
	v_readlane_b32 s67, v252, 7
	v_readlane_b32 s74, v252, 14
	v_readlane_b32 s75, v252, 15
	s_mov_b64 s[62:63], s[70:71]
	v_lshl_add_u64 v[4:5], v[4:5], 2, s[60:61]
	v_ashrrev_i32_e32 v7, 31, v6
	v_ashrrev_i32_e32 v9, 31, v8
	v_ashrrev_i32_e32 v11, 31, v10
	v_lshlrev_b64 v[2:3], 2, v[2:3]
	v_readlane_b32 s64, v252, 4
	v_readlane_b32 s65, v252, 5
	v_readlane_b32 s72, v252, 12
	v_readlane_b32 s73, v252, 13
	s_mov_b64 s[66:67], s[74:75]
	v_lshl_add_u64 v[6:7], v[6:7], 2, s[60:61]
	v_lshl_add_u64 v[8:9], v[8:9], 2, s[60:61]
	v_lshl_add_u64 v[10:11], v[10:11], 2, s[60:61]
	global_load_dword v50, v[4:5], off
	global_load_dword v51, v[6:7], off
	global_load_dword v53, v[8:9], off
	global_load_dword v52, v[10:11], off
	v_lshl_add_u64 v[4:5], s[62:63], 0, v[2:3]
	global_load_dword v106, v[4:5], off
	v_lshl_add_u64 v[4:5], s[66:67], 0, v[2:3]
	v_readlane_b32 s60, v252, 16
	v_readlane_b32 s62, v252, 18
	v_readlane_b32 s63, v252, 19
	v_readlane_b32 s64, v252, 20
	v_readlane_b32 s65, v252, 21
	global_load_dword v107, v[4:5], off
	v_lshl_add_u64 v[4:5], s[62:63], 0, v[2:3]
	v_lshl_add_u64 v[2:3], s[64:65], 0, v[2:3]
	global_load_dword v108, v[4:5], off
	global_load_dword v1, v[2:3], off
	v_readlane_b32 s61, v252, 17
	v_readlane_b32 s66, v252, 22
	v_readlane_b32 s67, v252, 23
	v_readlane_b32 s68, v252, 24
	v_readlane_b32 s69, v252, 25
	v_readlane_b32 s70, v252, 26
	v_readlane_b32 s71, v252, 27
	v_readlane_b32 s72, v252, 28
	v_readlane_b32 s73, v252, 29
	v_readlane_b32 s74, v252, 30
	v_readlane_b32 s75, v252, 31
	s_and_saveexec_b64 s[18:19], s[6:7]
	ds_write_b32 v192, v0
	s_or_b64 exec, exec, s[18:19]
	s_waitcnt vmcnt(0)
	v_mul_f32_e32 v2, 0xbfb8aa3b, v1
	v_rndne_f32_e32 v3, v2
	s_mov_b32 s0, 0xbfb8aa3b
	v_sub_f32_e32 v4, v2, v3
	v_fma_f32 v2, v1, s0, -v2
	v_fmac_f32_e32 v2, 0xb2a5705f, v1
	v_add_f32_e32 v2, v4, v2
	v_cvt_i32_f32_e32 v3, v3
	v_exp_f32_e32 v2, v2
	s_mov_b32 s0, 0x42ce8ed0
	v_cmp_nlt_f32_e32 vcc, s0, v1
	s_mov_b32 s0, 0xc2b17218
	v_ldexp_f32 v2, v2, v3
	v_cndmask_b32_e32 v2, 0, v2, vcc
	v_cmp_ngt_f32_e32 vcc, s0, v1
	s_mov_b32 s17, 0x3f2aaaab
	v_lshl_add_u32 v110, s1, 2, v196
	v_cndmask_b32_e32 v1, v225, v2, vcc
	v_add_f32_e32 v4, 1.0, v1
	v_add_f32_e32 v2, -1.0, v4
	v_sub_f32_e32 v3, v2, v4
	v_add_f32_e32 v3, 1.0, v3
	v_sub_f32_e32 v2, v1, v2
	v_add_f32_e32 v5, v2, v3
	v_frexp_mant_f32_e32 v6, v4
	v_cvt_f64_f32_e32 v[2:3], v4
	v_frexp_exp_i32_f64_e32 v2, v[2:3]
	v_cmp_gt_f32_e32 vcc, s17, v6
	s_mov_b32 s17, 0x3f317218
	s_mov_b32 s0, 0
	v_subbrev_co_u32_e32 v2, vcc, 0, v2, vcc
	v_sub_u32_e32 v3, 0, v2
	v_ldexp_f32 v4, v4, v3
	v_ldexp_f32 v3, v5, v3
	v_add_f32_e32 v5, -1.0, v4
	v_add_f32_e32 v8, 1.0, v4
	v_add_f32_e32 v6, 1.0, v5
	v_add_f32_e32 v9, -1.0, v8
	v_sub_f32_e32 v6, v4, v6
	v_sub_f32_e32 v4, v4, v9
	v_add_f32_e32 v6, v3, v6
	v_add_f32_e32 v3, v3, v4
	v_add_f32_e32 v4, v8, v3
	v_rcp_f32_e32 v9, v4
	v_add_f32_e32 v7, v5, v6
	v_sub_f32_e32 v5, v5, v7
	v_add_f32_e32 v5, v6, v5
	v_sub_f32_e32 v6, v8, v4
	v_add_f32_e32 v3, v3, v6
	v_mul_f32_e32 v6, v7, v9
	v_mul_f32_e32 v8, v4, v6
	v_fma_f32 v10, v6, v4, -v8
	v_fmac_f32_e32 v10, v6, v3
	v_add_f32_e32 v11, v8, v10
	v_sub_f32_e32 v12, v7, v11
	v_sub_f32_e32 v7, v7, v12
	v_sub_f32_e32 v8, v11, v8
	v_sub_f32_e32 v7, v7, v11
	v_add_f32_e32 v5, v5, v7
	v_sub_f32_e32 v7, v8, v10
	v_add_f32_e32 v5, v7, v5
	v_add_f32_e32 v7, v12, v5
	v_mul_f32_e32 v8, v9, v7
	v_mul_f32_e32 v10, v4, v8
	v_fma_f32 v4, v8, v4, -v10
	v_fmac_f32_e32 v4, v8, v3
	v_sub_f32_e32 v3, v12, v7
	v_add_f32_e32 v3, v5, v3
	v_add_f32_e32 v5, v10, v4
	v_sub_f32_e32 v11, v7, v5
	v_sub_f32_e32 v7, v7, v11
	v_sub_f32_e32 v10, v5, v10
	v_sub_f32_e32 v5, v7, v5
	v_add_f32_e32 v3, v3, v5
	v_sub_f32_e32 v4, v10, v4
	v_cvt_f32_i32_e32 v2, v2
	v_add_f32_e32 v3, v4, v3
	v_add_f32_e32 v4, v6, v8
	v_add_f32_e32 v3, v11, v3
	v_sub_f32_e32 v5, v4, v6
	v_mul_f32_e32 v3, v9, v3
	v_sub_f32_e32 v5, v8, v5
	v_add_f32_e32 v3, v5, v3
	v_mul_f32_e32 v8, 0x3f317218, v2
	v_add_f32_e32 v5, v4, v3
	v_fma_f32 v9, v2, s17, -v8
	v_mul_f32_e32 v6, v5, v5
	v_fmac_f32_e32 v9, 0xb102e308, v2
	v_sub_f32_e32 v2, v5, v4
	v_fmamk_f32 v7, v6, 0x3e9b6dac, v219
	v_sub_f32_e32 v2, v3, v2
	v_add_f32_e32 v3, v8, v9
	v_fmaak_f32 v7, v6, v7, 0x3f2aaada
	v_sub_f32_e32 v4, v3, v8
	v_ldexp_f32 v8, v5, 1
	v_mul_f32_e32 v5, v5, v6
	v_mul_f32_e32 v5, v5, v7
	v_add_f32_e32 v6, v8, v5
	v_sub_f32_e32 v7, v6, v8
	v_ldexp_f32 v2, v2, 1
	v_sub_f32_e32 v5, v5, v7
	v_add_f32_e32 v2, v2, v5
	v_add_f32_e32 v5, v6, v2
	v_sub_f32_e32 v6, v5, v6
	v_sub_f32_e32 v2, v2, v6
	v_add_f32_e32 v6, v3, v5
	v_sub_f32_e32 v7, v6, v3
	v_sub_f32_e32 v8, v6, v7
	v_sub_f32_e32 v4, v9, v4
	v_sub_f32_e32 v3, v3, v8
	v_sub_f32_e32 v5, v5, v7
	v_add_f32_e32 v3, v5, v3
	v_add_f32_e32 v5, v4, v2
	v_sub_f32_e32 v7, v5, v4
	v_sub_f32_e32 v8, v5, v7
	v_sub_f32_e32 v4, v4, v8
	v_sub_f32_e32 v2, v2, v7
	v_add_f32_e32 v3, v5, v3
	v_add_f32_e32 v2, v2, v4
	v_add_f32_e32 v4, v6, v3
	v_sub_f32_e32 v5, v4, v6
	v_sub_f32_e32 v3, v3, v5
	v_add_f32_e32 v2, v2, v3
	s_mov_b32 s17, 0x7f800000
	v_add_f32_e32 v2, v4, v2
	v_cmp_neq_f32_e32 vcc, s17, v1
	s_mov_b32 s17, 0x33800000
	v_add_u32_e32 v111, 0x4400, v110
	v_cndmask_b32_e32 v2, v225, v2, vcc
	v_cmp_lt_f32_e64 vcc, |v1|, s17
	s_ashr_i32 s17, s16, 31
	s_lshl_b64 s[16:17], s[16:17], 1
	v_cndmask_b32_e32 v1, v2, v1, vcc
	v_mul_f32_e32 v1, 0xc1000000, v1
	v_mul_f32_e32 v109, 0x3fb8aa3b, v1
	v_lshl_add_u64 v[54:55], v[156:157], 0, s[16:17]
	v_mov_b32_e32 v56, v53
	v_mov_b32_e32 v57, v52
	v_lshl_add_u64 v[58:59], v[158:159], 0, s[16:17]
	v_lshl_add_u64 v[60:61], v[164:165], 0, s[16:17]
	s_mov_b64 s[60:61], 0
	v_mov_b32_e32 v62, v216
	s_and_b32 s100, s2, 7
	s_lshl_b32 s100, s100, 23
	s_add_u32 s100, s100, s16
	s_add_u32 s98, s86, s100
	s_addc_u32 s99, s87, 0
	s_add_u32 s98, s98, 0x13ffe800
	s_addc_u32 s99, s99, 0
	v_lshrrev_b32_e32 v249, 4, v160
	v_and_b32_e32 v248, 15, v160
	v_lshlrev_b32_e32 v248, 4, v248
	v_lshl_add_u32 v248, v249, 11, v248
	v_lshrrev_b32_e32 v249, 6, v160
	s_nop 0
	v_readfirstlane_b32 s100, v249
	s_nop 3
	s_lshl_b32 s100, s100, 10
	s_add_u32 m0, s100, 0x16000
	s_mov_b32 s100, s98
	s_mov_b32 s101, s99
	global_load_lds_dwordx4 v248, s[100:101]
	s_add_u32 s100, s100, 0x10000
	s_addc_u32 s101, s101, 0
	s_add_u32 m0, m0, 0x2000
	s_nop 0
	global_load_lds_dwordx4 v248, s[100:101]
	s_cmp_eq_u32 m0, 0x18000
	s_cbranch_scc0 .Llru_dma_skip_L1p
	s_add_u32 s100, s100, 0x10000
	s_addc_u32 s101, s101, 0
	s_add_u32 m0, m0, 0x2000
	s_nop 0
	global_load_lds_dwordx4 v248, s[100:101]

.LBB0_1314:
	v_add_u32_e32 v1, s60, v162
	v_cmp_eq_u32_e64 s[16:17], 0, v1
	v_and_b32_e32 v248, 0x7f, v160
	v_lshrrev_b32_e32 v249, 7, v160
	v_lshlrev_b32_e32 v248, 1, v248
	v_lshl_add_u32 v248, v249, 12, v248
	v_add_u32_e32 v248, 0x16000, v248
	ds_read_u16 v4, v248
	ds_read_u16 v5, v248 offset:256
	ds_read_u16 v7, v248 offset:512
	ds_read_u16 v13, v248 offset:1280
	ds_read_u16 v14, v248 offset:1536
	ds_read_u16 v15, v248 offset:1792
	ds_read_u16 v16, v248 offset:2048
	ds_read_u16 v17, v248 offset:2304
	ds_read_u16 v66, v248 offset:2560
	v_lshl_add_u64 v[64:65], v[60:61], 0, s[60:61]
	v_add_co_u32_e32 v8, vcc, 0x18000000, v64
	s_nop 0
	v_addc_co_u32_e32 v9, vcc, 0, v65, vcc
	global_load_ushort v126, v[8:9], off
	global_load_ushort v125, v[8:9], off offset:2048
	v_add_co_u32_e32 v8, vcc, 0x18001000, v64
	v_lshl_add_u64 v[2:3], v[58:59], 0, s[60:61]
	s_nop 0
	v_addc_co_u32_e32 v9, vcc, 0, v65, vcc
	global_load_ushort v124, v[8:9], off
	global_load_ushort v123, v[8:9], off offset:2048
	v_add_co_u32_e32 v8, vcc, 0x18002000, v64
	s_brev_b32 s1, 40
	s_nop 0
	v_addc_co_u32_e32 v9, vcc, 0, v65, vcc
	global_load_ushort v122, v[8:9], off
	global_load_ushort v121, v[8:9], off offset:2048
	v_add_co_u32_e32 v8, vcc, 0x18003000, v64
	s_nop 1
	v_addc_co_u32_e32 v9, vcc, 0, v65, vcc
	global_load_ushort v120, v[8:9], off
	global_load_ushort v119, v[8:9], off offset:2048
	v_add_co_u32_e32 v8, vcc, 0x18004000, v64
	s_nop 1
	v_addc_co_u32_e32 v9, vcc, 0, v65, vcc
	global_load_ushort v118, v[8:9], off
	global_load_ushort v117, v[8:9], off offset:2048
	v_add_co_u32_e32 v8, vcc, 0x18005000, v64
	s_nop 1
	v_addc_co_u32_e32 v9, vcc, 0, v65, vcc
	global_load_ushort v116, v[8:9], off
	global_load_ushort v115, v[8:9], off offset:2048
	v_add_co_u32_e32 v8, vcc, 0x18006000, v64
	s_nop 1
	v_addc_co_u32_e32 v9, vcc, 0, v65, vcc
	global_load_ushort v114, v[8:9], off
	global_load_ushort v113, v[8:9], off offset:2048
	v_add_co_u32_e32 v8, vcc, 0x18007000, v64
	s_nop 1
	v_addc_co_u32_e32 v9, vcc, 0, v65, vcc
	global_load_ushort v112, v[8:9], off
	global_load_ushort v63, v[8:9], off offset:2048
	s_waitcnt lgkmcnt(6)
	ds_read_u16 v70, v248 offset:2816
	ds_read_u16 v71, v248 offset:3072
	ds_read_u16 v72, v248 offset:3328
	ds_read_u16 v73, v248 offset:3584
	ds_read_u16 v74, v248 offset:3840
	ds_read_u16 v75, v248 offset:4096
	ds_read_u16 v83, v248 offset:4352
	ds_read_u16 v82, v248 offset:4608
	s_waitcnt lgkmcnt(0)
	v_lshlrev_b32_e32 v4, 16, v4
	v_lshlrev_b32_e32 v5, 16, v5
	v_lshlrev_b32_e32 v7, 16, v7
	v_cndmask_b32_e64 v4, v4, 0, s[16:17]
	v_cndmask_b32_e64 v5, v5, 0, s[16:17]
	v_cndmask_b32_e64 v7, v7, 0, s[16:17]
	v_mov_b32_e32 v6, v5
	v_pk_mul_f32 v[8:9], v[50:51], v[4:5]
	v_pk_mul_f32 v[4:5], v[50:51], v[6:7]
	v_add_f32_e32 v1, v106, v8
	v_add_f32_e32 v4, v106, v4
	v_add_f32_e32 v12, v4, v5
	v_add_co_u32_e32 v4, vcc, s1, v2
	s_mov_b32 s1, 0x14001000
	s_nop 0
	v_addc_co_u32_e32 v5, vcc, 0, v3, vcc
	v_add_co_u32_e32 v8, vcc, s1, v2
	v_add_f32_e32 v1, v1, v9
	s_nop 0
	v_addc_co_u32_e32 v9, vcc, 0, v3, vcc
	ds_read_u16 v6, v248 offset:768
	s_nop 0
	ds_read_u16 v4, v248 offset:1024
	s_nop 0
	s_mov_b32 s1, 0x14002000
	v_add_co_u32_e32 v8, vcc, s1, v2
	s_mov_b32 s1, 0x14003000
	s_nop 0
	v_addc_co_u32_e32 v9, vcc, 0, v3, vcc
	s_waitcnt lgkmcnt(0)
	v_lshlrev_b32_e32 v5, 16, v4
	v_lshlrev_b32_e32 v4, 16, v6
	v_mov_b32_e32 v6, v7
	v_mov_b32_e32 v7, v4
	v_pk_mul_f32 v[10:11], v[56:57], v[6:7]
	v_pk_mul_f32 v[6:7], v[50:51], v[6:7]
	v_add_f32_e32 v1, v1, v10
	v_add_co_u32_e32 v10, vcc, s1, v2
	v_add_f32_e32 v67, v1, v11
	s_nop 0
	v_addc_co_u32_e32 v11, vcc, 0, v3, vcc
	s_mov_b32 s1, 0x14004000
	v_add_co_u32_e32 v8, vcc, s1, v2
	s_mov_b32 s1, 0x14005000
	s_nop 0
	v_addc_co_u32_e32 v9, vcc, 0, v3, vcc
	v_add_co_u32_e32 v10, vcc, s1, v2
	s_mov_b32 s1, 0x14006000
	s_nop 0
	v_addc_co_u32_e32 v11, vcc, 0, v3, vcc
	v_add_co_u32_e32 v8, vcc, s1, v2
	s_mov_b32 s1, 0x14007000
	s_nop 0
	v_addc_co_u32_e32 v9, vcc, 0, v3, vcc
	v_add_co_u32_e32 v2, vcc, s1, v2
	v_cvt_pk_bf16_f32 v1, v67, s0
	s_nop 0
	v_addc_co_u32_e32 v3, vcc, 0, v3, vcc
	v_pk_mul_f32 v[2:3], v[56:57], v[4:5]
	ds_write_b16 v220, v1
	v_add_f32_e32 v1, v12, v2
	v_add_f32_e32 v2, v106, v6
	v_add_f32_e32 v2, v2, v7
	v_pk_mul_f32 v[6:7], v[50:51], v[4:5]
	v_mov_b32_e32 v9, v5
	v_add_f32_e32 v6, v106, v6
	v_add_f32_e32 v12, v6, v7
	v_lshlrev_b32_e32 v7, 16, v14
	v_lshlrev_b32_e32 v6, 16, v13
	v_pk_mov_b32 v[4:5], v[4:5], v[6:7] op_sel:[1,0]
	v_mov_b32_e32 v8, v6
	v_pk_mul_f32 v[4:5], v[50:51], v[4:5]
	v_pk_mul_f32 v[8:9], v[52:53], v[8:9]
	v_pk_mul_f32 v[10:11], v[56:57], v[6:7]
	v_add_f32_e32 v4, v106, v4
	v_add_f32_e32 v2, v9, v2
	v_add_f32_e32 v9, v10, v12
	v_add_f32_e32 v10, v4, v5
	v_pk_mul_f32 v[4:5], v[50:51], v[6:7]
	v_mov_b32_e32 v13, v7
	v_add_f32_e32 v4, v106, v4
	v_add_f32_e32 v68, v4, v5
	v_add_f32_e32 v90, v11, v9
	v_add_f32_e32 v92, v8, v2
	v_add_f32_e32 v94, v3, v1
	v_cvt_pk_bf16_f32 v2, v92, s0
	v_cvt_pk_bf16_f32 v1, v94, s0
	ds_write_b16 v221, v2 offset:272
	ds_write_b16 v221, v1
	s_and_b32 s1, s0, 0x80
	v_lshlrev_b32_e32 v4, 16, v15
	v_lshlrev_b32_e32 v5, 16, v16
	v_pk_mov_b32 v[6:7], v[6:7], v[4:5] op_sel:[1,0]
	v_mov_b32_e32 v12, v4
	v_pk_mul_f32 v[6:7], v[50:51], v[6:7]
	v_pk_mul_f32 v[12:13], v[52:53], v[12:13]
	v_pk_mul_f32 v[14:15], v[56:57], v[4:5]
	v_add_f32_e32 v6, v106, v6
	v_add_f32_e32 v10, v13, v10
	v_add_f32_e32 v13, v14, v68
	v_add_f32_e32 v14, v6, v7
	v_pk_mul_f32 v[6:7], v[50:51], v[4:5]
	v_add_f32_e32 v86, v15, v13
	v_add_f32_e32 v6, v106, v6
	v_add_f32_e32 v76, v6, v7
	v_lshlrev_b32_e32 v7, 16, v66
	v_lshlrev_b32_e32 v6, 16, v17
	v_mov_b32_e32 v17, v5
	v_pk_mov_b32 v[4:5], v[4:5], v[6:7] op_sel:[1,0]
	v_mov_b32_e32 v16, v6
	v_pk_mul_f32 v[4:5], v[50:51], v[4:5]
	v_pk_mul_f32 v[16:17], v[52:53], v[16:17]
	v_add_f32_e32 v4, v106, v4
	v_add_f32_e32 v66, v4, v5
	v_pk_mul_f32 v[4:5], v[50:51], v[6:7]
	v_pk_mul_f32 v[68:69], v[56:57], v[6:7]
	v_add_f32_e32 v4, v106, v4
	v_add_f32_e32 v14, v17, v14
	v_add_f32_e32 v17, v68, v76
	v_add_f32_e32 v68, v4, v5
	v_lshlrev_b32_e32 v5, 16, v71
	v_lshlrev_b32_e32 v4, 16, v70
	v_mov_b32_e32 v71, v7
	v_pk_mov_b32 v[6:7], v[6:7], v[4:5] op_sel:[1,0]
	v_mov_b32_e32 v70, v4
	v_pk_mul_f32 v[6:7], v[50:51], v[6:7]
	v_pk_mul_f32 v[78:79], v[52:53], v[70:71]
	v_add_f32_e32 v6, v106, v6
	v_add_f32_e32 v79, v79, v66
	v_add_f32_e32 v66, v6, v7
	v_pk_mul_f32 v[6:7], v[50:51], v[4:5]
	v_pk_mul_f32 v[70:71], v[56:57], v[4:5]
	v_add_f32_e32 v6, v106, v6
	v_add_f32_e32 v84, v70, v68
	v_add_f32_e32 v68, v6, v7
	v_lshlrev_b32_e32 v7, 16, v73
	v_lshlrev_b32_e32 v6, 16, v72
	v_mov_b32_e32 v73, v5
	v_pk_mov_b32 v[4:5], v[4:5], v[6:7] op_sel:[1,0]
	v_mov_b32_e32 v72, v6
	v_pk_mul_f32 v[4:5], v[50:51], v[4:5]
	v_pk_mul_f32 v[76:77], v[52:53], v[72:73]
	v_add_f32_e32 v4, v106, v4
	v_add_f32_e32 v77, v77, v66
	v_add_f32_e32 v66, v4, v5
	v_pk_mul_f32 v[4:5], v[50:51], v[6:7]
	v_pk_mul_f32 v[72:73], v[56:57], v[6:7]
	v_add_f32_e32 v4, v106, v4
	v_add_f32_e32 v85, v72, v68
	v_add_f32_e32 v68, v4, v5
	v_lshlrev_b32_e32 v5, 16, v75
	v_lshlrev_b32_e32 v4, 16, v74
	v_mov_b32_e32 v75, v7
	v_pk_mov_b32 v[6:7], v[6:7], v[4:5] op_sel:[1,0]
	v_mov_b32_e32 v74, v4
	v_pk_mul_f32 v[6:7], v[50:51], v[6:7]
	v_pk_mul_f32 v[74:75], v[52:53], v[74:75]
	v_add_f32_e32 v6, v106, v6
	v_add_f32_e32 v72, v75, v66
	v_add_f32_e32 v66, v6, v7
	v_pk_mul_f32 v[6:7], v[50:51], v[4:5]
	v_pk_mul_f32 v[80:81], v[56:57], v[4:5]
	v_add_f32_e32 v4, v106, v6
	v_add_f32_e32 v70, v80, v68
	v_add_f32_e32 v68, v4, v7
	v_lshlrev_b32_e32 v7, 16, v83
	v_mov_b32_e32 v4, v7
	v_lshlrev_b32_e32 v6, 16, v82
	v_pk_mul_f32 v[4:5], v[52:53], v[4:5]
	v_pk_mul_f32 v[6:7], v[52:53], v[6:7]
	v_add_f32_e32 v5, v5, v66
	v_add_f32_e32 v7, v7, v68
	v_add_f32_e32 v68, v4, v5
	v_cvt_pk_bf16_f32 v4, v68, s0
	v_add_f32_e32 v70, v81, v70
	ds_write_b16 v221, v4 offset:3536
	v_cvt_pk_bf16_f32 v4, v70, s0
	v_add_f32_e32 v72, v74, v72
	ds_write_b16 v221, v4 offset:3264
	v_cvt_pk_bf16_f32 v4, v72, s0
	v_add_f32_e32 v74, v73, v85
	ds_write_b16 v221, v4 offset:2992
	v_cvt_pk_bf16_f32 v4, v74, s0
	v_add_f32_e32 v76, v76, v77
	ds_write_b16 v221, v4 offset:2720
	v_cvt_pk_bf16_f32 v4, v76, s0
	v_add_f32_e32 v80, v71, v84
	ds_write_b16 v221, v4 offset:2448
	v_cvt_pk_bf16_f32 v4, v80, s0
	v_add_f32_e32 v82, v78, v79
	ds_write_b16 v221, v4 offset:2176
	v_cvt_pk_bf16_f32 v4, v82, s0
	v_add_f32_e32 v78, v69, v17
	ds_write_b16 v221, v4 offset:1904
	v_cvt_pk_bf16_f32 v4, v78, s0
	v_add_f32_e32 v84, v16, v14
	ds_write_b16 v221, v4 offset:1632
	v_cvt_pk_bf16_f32 v4, v84, s0
	ds_write_b16 v221, v4 offset:1360
	v_cvt_pk_bf16_f32 v4, v86, s0
	v_add_f32_e32 v88, v12, v10
	v_add_f32_e32 v66, v6, v7
	ds_write_b16 v221, v4 offset:1088
	v_cvt_pk_bf16_f32 v4, v88, s0
	v_cvt_pk_bf16_f32 v6, v66, s0
	ds_write_b16 v221, v4 offset:816
	v_cvt_pk_bf16_f32 v4, v90, s0
	ds_write_b16 v221, v6 offset:3808
	ds_write_b16 v221, v4 offset:544
	s_waitcnt lgkmcnt(0)
	s_barrier
	v_lshrrev_b32_e32 v249, 4, v160
	v_and_b32_e32 v248, 15, v160
	v_lshlrev_b32_e32 v248, 4, v248
	v_lshl_add_u32 v248, v249, 11, v248
	v_lshrrev_b32_e32 v249, 6, v160
	s_nop 0
	v_readfirstlane_b32 s100, v249
	s_nop 3
	s_lshl_b32 s100, s100, 10
	s_add_u32 m0, s100, 0x16000
	s_add_u32 s100, s98, s60
	s_addc_u32 s101, s99, s61
	s_add_u32 s100, s100, 0x20000
	s_addc_u32 s101, s101, 0
	global_load_lds_dwordx4 v248, s[100:101]
	s_add_u32 s100, s100, 0x10000
	s_addc_u32 s101, s101, 0
	s_add_u32 m0, m0, 0x2000
	s_nop 0
	global_load_lds_dwordx4 v248, s[100:101]
	s_cmp_eq_u32 m0, 0x18000
	s_cbranch_scc0 .Llru_dma_skip_L1
	s_add_u32 s100, s100, 0x10000
	s_addc_u32 s101, s101, 0
	s_add_u32 m0, m0, 0x2000
	s_nop 0
	global_load_lds_dwordx4 v248, s[100:101]
.Llru_dma_skip_L1:
	ds_read_b128 v[2:5], v222
	ds_read_b128 v[96:99], v222 offset:32
	s_waitcnt lgkmcnt(1)
	v_mfma_f32_32x32x16_bf16 v[2:17], v[2:5], v[18:21], 0
	s_waitcnt lgkmcnt(0)
	v_mfma_f32_32x32x16_bf16 v[2:17], v[96:99], v[22:25], v[2:17]
	ds_read_b128 v[96:99], v222 offset:64
	s_waitcnt lgkmcnt(0)
	v_mfma_f32_32x32x16_bf16 v[2:17], v[96:99], v[26:29], v[2:17]
	ds_read_b128 v[96:99], v222 offset:96
	s_waitcnt lgkmcnt(0)
	v_mfma_f32_32x32x16_bf16 v[2:17], v[96:99], v[30:33], v[2:17]
	ds_read_b128 v[96:99], v222 offset:128
	s_waitcnt lgkmcnt(0)
	v_mfma_f32_32x32x16_bf16 v[2:17], v[96:99], v[34:37], v[2:17]
	ds_read_b128 v[96:99], v222 offset:160
	s_waitcnt lgkmcnt(0)
	v_mfma_f32_32x32x16_bf16 v[2:17], v[96:99], v[38:41], v[2:17]
	ds_read_b128 v[96:99], v222 offset:192
	s_waitcnt lgkmcnt(0)
	v_mfma_f32_32x32x16_bf16 v[2:17], v[96:99], v[42:45], v[2:17]
	ds_read_b128 v[96:99], v222 offset:224
	s_waitcnt lgkmcnt(0)
	v_mfma_f32_32x32x16_bf16 v[2:17], v[96:99], v[46:49], v[2:17]
	s_nop 11
	ds_write_b32 v110, v2 offset:17408
	ds_write_b32 v110, v3 offset:18448
	ds_write_b32 v110, v4 offset:19488
	ds_write_b32 v110, v5 offset:20528
	ds_write_b32 v110, v6 offset:25728
	ds_write_b32 v110, v7 offset:26768
	ds_write_b32 v110, v8 offset:27808
	ds_write_b32 v110, v9 offset:28848
	ds_write_b32 v110, v10 offset:34048
	ds_write_b32 v110, v11 offset:35088
	ds_write_b32 v110, v12 offset:36128
	ds_write_b32 v110, v13 offset:37168
	ds_write_b32 v110, v14 offset:42368
	ds_write_b32 v110, v15 offset:43408
	ds_write_b32 v110, v16 offset:44448
	ds_write_b32 v110, v17 offset:45488
	ds_read_b128 v[2:5], v222 offset:8704
	ds_read_b128 v[96:99], v222 offset:8736
	s_waitcnt lgkmcnt(1)
	v_mfma_f32_32x32x16_bf16 v[2:17], v[2:5], v[18:21], 0
	s_waitcnt lgkmcnt(0)
	v_mfma_f32_32x32x16_bf16 v[2:17], v[96:99], v[22:25], v[2:17]
	ds_read_b128 v[96:99], v222 offset:8768
	s_waitcnt lgkmcnt(0)
	v_mfma_f32_32x32x16_bf16 v[2:17], v[96:99], v[26:29], v[2:17]
	ds_read_b128 v[96:99], v222 offset:8800
	s_waitcnt lgkmcnt(0)
	v_mfma_f32_32x32x16_bf16 v[2:17], v[96:99], v[30:33], v[2:17]
	ds_read_b128 v[96:99], v222 offset:8832
	s_waitcnt lgkmcnt(0)
	v_mfma_f32_32x32x16_bf16 v[2:17], v[96:99], v[34:37], v[2:17]
	ds_read_b128 v[96:99], v222 offset:8864
	s_waitcnt lgkmcnt(0)
	v_mfma_f32_32x32x16_bf16 v[2:17], v[96:99], v[38:41], v[2:17]
	ds_read_b128 v[96:99], v222 offset:8896
	s_waitcnt lgkmcnt(0)
	v_mfma_f32_32x32x16_bf16 v[2:17], v[96:99], v[42:45], v[2:17]
	ds_read_b128 v[96:99], v222 offset:8928
	s_waitcnt lgkmcnt(0)
	v_mfma_f32_32x32x16_bf16 v[2:17], v[96:99], v[46:49], v[2:17]
	s_nop 11
	ds_write_b32 v110, v2 offset:50688
	ds_write_b32 v110, v3 offset:51728
	ds_write_b32 v110, v4 offset:52768
	ds_write_b32 v110, v5 offset:53808
	ds_write_b32 v110, v6 offset:59008
	ds_write_b32 v110, v7 offset:60048
	ds_write_b32 v110, v8 offset:61088
	ds_write_b32 v110, v9 offset:62128
	ds_write_b32 v111, v10 offset:49920
	ds_write_b32 v111, v11 offset:50960
	ds_write_b32 v111, v12 offset:52000
	ds_write_b32 v111, v13 offset:53040
	ds_write_b32 v111, v14 offset:58240
	ds_write_b32 v111, v15 offset:59280
	ds_write_b32 v111, v16 offset:60320
	ds_write_b32 v111, v17 offset:61360
	s_waitcnt lgkmcnt(0)
	s_barrier
	ds_read2st64_b32 v[2:3], v197 offset0:68 offset1:70
	s_waitcnt lgkmcnt(0)
	v_add_f32_e32 v1, v107, v2
	v_mul_f32_e32 v1, 0xbfb8aa3b, v1
	v_exp_f32_e32 v1, v1
	v_add_f32_e32 v2, v108, v3
	v_mul_f32_e32 v2, 0xbfb8aa3b, v2
	v_exp_f32_e32 v2, v2
	v_add_f32_e32 v1, 1.0, v1
	v_rcp_f32_e32 v1, v1
	v_add_f32_e32 v2, 1.0, v2
	v_rcp_f32_e32 v3, v2
	v_mul_f32_e32 v1, v109, v1
	v_exp_f32_e32 v2, v1
	v_mul_f32_e32 v3, v67, v3
	v_fma_f32 v1, -v2, v2, 1.0
	v_max_f32_e32 v1, 0, v1
	v_cmp_gt_f32_e32 vcc, s79, v1
	v_mul_f32_e32 v4, 0x4f800000, v1
	s_nop 0
	v_cndmask_b32_e32 v1, v1, v4, vcc
	v_sqrt_f32_e32 v4, v1
	s_nop 0
	v_add_u32_e32 v5, -1, v4
	v_fma_f32 v6, -v5, v4, v1
	v_cmp_ge_f32_e64 s[18:19], 0, v6
	v_add_u32_e32 v6, 1, v4
	s_nop 0
	v_cndmask_b32_e64 v5, v4, v5, s[18:19]
	v_fma_f32 v4, -v6, v4, v1
	v_cmp_lt_f32_e64 s[18:19], 0, v4
	s_nop 1
	v_cndmask_b32_e64 v4, v5, v6, s[18:19]
	v_mul_f32_e32 v5, 0x37800000, v4
	ds_read2st64_b32 v[6:7], v198 offset0:68 offset1:70
	v_cndmask_b32_e32 v4, v4, v5, vcc
	v_cmp_class_f32_e32 vcc, v1, v217
	s_nop 1
	v_cndmask_b32_e32 v1, v4, v1, vcc
	v_cndmask_b32_e64 v1, v1, 1.0, s[16:17]
	v_mul_f32_e32 v4, v3, v1
	v_pk_fma_f32 v[4:5], v[2:3], v[0:1], v[4:5] op_sel_hi:[1,1,0]
	s_waitcnt lgkmcnt(0)
	v_add_f32_e32 v1, v107, v6
	v_mul_f32_e32 v1, 0xbfb8aa3b, v1
	v_exp_f32_e32 v1, v1
	v_add_f32_e32 v3, v108, v7
	v_mul_f32_e32 v3, 0xbfb8aa3b, v3
	v_exp_f32_e32 v3, v3
	v_add_f32_e32 v1, 1.0, v1
	v_rcp_f32_e32 v1, v1
	v_mov_b32_e32 v95, v4
	v_add_f32_e32 v3, 1.0, v3
	v_rcp_f32_e32 v8, v3
	v_mul_f32_e32 v1, v109, v1
	v_exp_f32_e32 v9, v1
	s_nop 0
	v_fma_f32 v1, -v9, v9, 1.0
	v_max_f32_e32 v1, 0, v1
	v_cmp_gt_f32_e32 vcc, s79, v1
	v_mul_f32_e32 v3, 0x4f800000, v1
	s_nop 0
	v_cndmask_b32_e32 v1, v1, v3, vcc
	v_sqrt_f32_e32 v3, v1
	s_nop 0
	v_add_u32_e32 v5, -1, v3
	v_fma_f32 v6, -v5, v3, v1
	v_cmp_ge_f32_e64 s[16:17], 0, v6
	v_add_u32_e32 v6, 1, v3
	s_nop 0
	v_cndmask_b32_e64 v5, v3, v5, s[16:17]
	v_fma_f32 v3, -v6, v3, v1
	v_cmp_lt_f32_e64 s[16:17], 0, v3
	s_nop 1
	v_cndmask_b32_e64 v3, v5, v6, s[16:17]
	v_mul_f32_e32 v5, 0x37800000, v3
	v_cndmask_b32_e32 v3, v3, v5, vcc
	v_cmp_class_f32_e32 vcc, v1, v217
	v_pk_mul_f32 v[6:7], v[94:95], v[8:9]
	s_nop 0
	v_cndmask_b32_e32 v1, v3, v1, vcc
	v_fmac_f32_e32 v7, v6, v1
	v_mul_f32_e32 v1, v2, v9
	ds_read2st64_b32 v[8:9], v199 offset0:68 offset1:70
	v_mov_b32_e32 v93, v7
	s_waitcnt lgkmcnt(0)
	v_add_f32_e32 v3, v107, v8
	v_mul_f32_e32 v3, 0xbfb8aa3b, v3
	v_exp_f32_e32 v3, v3
	v_add_f32_e32 v5, v108, v9
	v_mul_f32_e32 v5, 0xbfb8aa3b, v5
	v_exp_f32_e32 v5, v5
	v_add_f32_e32 v3, 1.0, v3
	v_rcp_f32_e32 v3, v3
	v_add_f32_e32 v5, 1.0, v5
	v_rcp_f32_e32 v10, v5
	v_mul_f32_e32 v3, v109, v3
	v_exp_f32_e32 v11, v3
	s_nop 0
	v_fma_f32 v3, -v11, v11, 1.0
	v_max_f32_e32 v3, 0, v3
	v_cmp_gt_f32_e32 vcc, s79, v3
	v_mul_f32_e32 v5, 0x4f800000, v3
	s_nop 0
	v_cndmask_b32_e32 v3, v3, v5, vcc
	v_sqrt_f32_e32 v5, v3
	s_nop 0
	v_add_u32_e32 v6, -1, v5
	v_fma_f32 v8, -v6, v5, v3
	v_cmp_ge_f32_e64 s[16:17], 0, v8
	v_add_u32_e32 v8, 1, v5
	s_nop 0
	v_cndmask_b32_e64 v6, v5, v6, s[16:17]
	v_fma_f32 v5, -v8, v5, v3
	v_cmp_lt_f32_e64 s[16:17], 0, v5
	s_nop 1
	v_cndmask_b32_e64 v5, v6, v8, s[16:17]
	v_mul_f32_e32 v6, 0x37800000, v5
	v_cndmask_b32_e32 v5, v5, v6, vcc
	v_cmp_class_f32_e32 vcc, v3, v217
	v_pk_mul_f32 v[8:9], v[92:93], v[10:11]
	s_nop 0
	v_cndmask_b32_e32 v3, v5, v3, vcc
	v_fmac_f32_e32 v9, v8, v3
	v_mul_f32_e32 v3, v1, v11
	ds_read2st64_b32 v[10:11], v200 offset0:68 offset1:70
	v_mov_b32_e32 v91, v9
	s_waitcnt lgkmcnt(0)
	v_add_f32_e32 v5, v107, v10
	v_mul_f32_e32 v5, 0xbfb8aa3b, v5
	v_exp_f32_e32 v5, v5
	v_add_f32_e32 v6, v108, v11
	v_mul_f32_e32 v6, 0xbfb8aa3b, v6
	v_exp_f32_e32 v6, v6
	v_add_f32_e32 v5, 1.0, v5
	v_rcp_f32_e32 v5, v5
	v_add_f32_e32 v6, 1.0, v6
	v_rcp_f32_e32 v12, v6
	v_mul_f32_e32 v5, v109, v5
	v_exp_f32_e32 v13, v5
	s_nop 0
	v_fma_f32 v5, -v13, v13, 1.0
	v_max_f32_e32 v5, 0, v5
	v_cmp_gt_f32_e32 vcc, s79, v5
	v_mul_f32_e32 v6, 0x4f800000, v5
	s_nop 0
	v_cndmask_b32_e32 v5, v5, v6, vcc
	v_sqrt_f32_e32 v6, v5
	s_nop 0
	v_add_u32_e32 v8, -1, v6
	v_fma_f32 v10, -v8, v6, v5
	v_cmp_ge_f32_e64 s[16:17], 0, v10
	v_add_u32_e32 v10, 1, v6
	s_nop 0
	v_cndmask_b32_e64 v8, v6, v8, s[16:17]
	v_fma_f32 v6, -v10, v6, v5
	v_cmp_lt_f32_e64 s[16:17], 0, v6
	s_nop 1
	v_cndmask_b32_e64 v6, v8, v10, s[16:17]
	v_mul_f32_e32 v8, 0x37800000, v6
	v_cndmask_b32_e32 v6, v6, v8, vcc
	v_cmp_class_f32_e32 vcc, v5, v217
	v_pk_mul_f32 v[10:11], v[90:91], v[12:13]
	s_nop 0
	v_cndmask_b32_e32 v5, v6, v5, vcc
	v_fmac_f32_e32 v11, v10, v5
	v_mul_f32_e32 v5, v3, v13
	ds_read2st64_b32 v[12:13], v201 offset0:68 offset1:70
	v_mov_b32_e32 v89, v11
	s_waitcnt lgkmcnt(0)
	v_add_f32_e32 v6, v107, v12
	v_mul_f32_e32 v6, 0xbfb8aa3b, v6
	v_exp_f32_e32 v6, v6
	v_add_f32_e32 v8, v108, v13
	v_mul_f32_e32 v8, 0xbfb8aa3b, v8
	v_exp_f32_e32 v8, v8
	v_add_f32_e32 v6, 1.0, v6
	v_rcp_f32_e32 v6, v6
	v_add_f32_e32 v8, 1.0, v8
	v_rcp_f32_e32 v14, v8
	v_mul_f32_e32 v6, v109, v6
	v_exp_f32_e32 v15, v6
	s_nop 0
	v_fma_f32 v6, -v15, v15, 1.0
	v_max_f32_e32 v6, 0, v6
	v_cmp_gt_f32_e32 vcc, s79, v6
	v_mul_f32_e32 v8, 0x4f800000, v6
	s_nop 0
	v_cndmask_b32_e32 v6, v6, v8, vcc
	v_sqrt_f32_e32 v8, v6
	s_nop 0
	v_add_u32_e32 v10, -1, v8
	v_fma_f32 v12, -v10, v8, v6
	v_cmp_ge_f32_e64 s[16:17], 0, v12
	v_add_u32_e32 v12, 1, v8
	s_nop 0
	v_cndmask_b32_e64 v10, v8, v10, s[16:17]
	v_fma_f32 v8, -v12, v8, v6
	v_cmp_lt_f32_e64 s[16:17], 0, v8
	s_nop 1
	v_cndmask_b32_e64 v8, v10, v12, s[16:17]
	v_mul_f32_e32 v10, 0x37800000, v8
	v_cndmask_b32_e32 v8, v8, v10, vcc
	v_cmp_class_f32_e32 vcc, v6, v217
	v_pk_mul_f32 v[12:13], v[88:89], v[14:15]
	s_nop 0
	v_cndmask_b32_e32 v6, v8, v6, vcc
	v_fmac_f32_e32 v13, v12, v6
	v_mul_f32_e32 v6, v5, v15
	ds_read2st64_b32 v[14:15], v202 offset0:68 offset1:70
	v_mov_b32_e32 v87, v13
	s_waitcnt lgkmcnt(0)
	v_add_f32_e32 v8, v107, v14
	v_mul_f32_e32 v8, 0xbfb8aa3b, v8
	v_exp_f32_e32 v8, v8
	v_add_f32_e32 v10, v108, v15
	v_mul_f32_e32 v10, 0xbfb8aa3b, v10
	v_exp_f32_e32 v10, v10
	v_add_f32_e32 v8, 1.0, v8
	v_rcp_f32_e32 v8, v8
	v_add_f32_e32 v10, 1.0, v10
	v_rcp_f32_e32 v16, v10
	v_mul_f32_e32 v8, v109, v8
	v_exp_f32_e32 v17, v8
	s_nop 0
	v_fma_f32 v8, -v17, v17, 1.0
	v_max_f32_e32 v8, 0, v8
	v_cmp_gt_f32_e32 vcc, s79, v8
	v_mul_f32_e32 v10, 0x4f800000, v8
	s_nop 0
	v_cndmask_b32_e32 v8, v8, v10, vcc
	v_sqrt_f32_e32 v10, v8
	s_nop 0
	v_add_u32_e32 v12, -1, v10
	v_fma_f32 v14, -v12, v10, v8
	v_cmp_ge_f32_e64 s[16:17], 0, v14
	v_add_u32_e32 v14, 1, v10
	s_nop 0
	v_cndmask_b32_e64 v12, v10, v12, s[16:17]
	v_fma_f32 v10, -v14, v10, v8
	v_cmp_lt_f32_e64 s[16:17], 0, v10
	s_nop 1
	v_cndmask_b32_e64 v10, v12, v14, s[16:17]
	v_mul_f32_e32 v12, 0x37800000, v10
	v_cndmask_b32_e32 v10, v10, v12, vcc
	v_cmp_class_f32_e32 vcc, v8, v217
	v_pk_mul_f32 v[14:15], v[86:87], v[16:17]
	s_nop 0
	v_cndmask_b32_e32 v8, v10, v8, vcc
	v_fmac_f32_e32 v15, v14, v8
	v_mul_f32_e32 v8, v6, v17
	ds_read2st64_b32 v[16:17], v203 offset0:68 offset1:70
	v_mov_b32_e32 v85, v15
	s_waitcnt lgkmcnt(0)
	v_add_f32_e32 v10, v107, v16
	v_mul_f32_e32 v10, 0xbfb8aa3b, v10
	v_exp_f32_e32 v10, v10
	v_add_f32_e32 v12, v108, v17
	v_mul_f32_e32 v12, 0xbfb8aa3b, v12
	v_exp_f32_e32 v12, v12
	v_add_f32_e32 v10, 1.0, v10
	v_rcp_f32_e32 v10, v10
	v_add_f32_e32 v12, 1.0, v12
	v_rcp_f32_e32 v86, v12
	v_mul_f32_e32 v10, v109, v10
	v_exp_f32_e32 v87, v10
	s_nop 0
	v_fma_f32 v10, -v87, v87, 1.0
	v_max_f32_e32 v10, 0, v10
	v_cmp_gt_f32_e32 vcc, s79, v10
	v_mul_f32_e32 v12, 0x4f800000, v10
	s_nop 0
	v_cndmask_b32_e32 v10, v10, v12, vcc
	v_sqrt_f32_e32 v12, v10
	s_nop 0
	v_add_u32_e32 v14, -1, v12
	v_fma_f32 v16, -v14, v12, v10
	v_cmp_ge_f32_e64 s[16:17], 0, v16
	v_add_u32_e32 v16, 1, v12
	s_nop 0
	v_cndmask_b32_e64 v14, v12, v14, s[16:17]
	v_fma_f32 v12, -v16, v12, v10
	v_cmp_lt_f32_e64 s[16:17], 0, v12
	s_nop 1
	v_cndmask_b32_e64 v12, v14, v16, s[16:17]
	v_pk_mul_f32 v[16:17], v[84:85], v[86:87]
	ds_read2st64_b32 v[84:85], v204 offset0:68 offset1:70
	v_mul_f32_e32 v14, 0x37800000, v12
	v_cndmask_b32_e32 v12, v12, v14, vcc
	v_cmp_class_f32_e32 vcc, v10, v217
	s_waitcnt lgkmcnt(0)
	v_add_f32_e32 v14, v108, v85
	v_cndmask_b32_e32 v10, v12, v10, vcc
	v_add_f32_e32 v12, v107, v84
	v_mul_f32_e32 v12, 0xbfb8aa3b, v12
	v_exp_f32_e32 v12, v12
	v_mul_f32_e32 v14, 0xbfb8aa3b, v14
	v_exp_f32_e32 v14, v14
	v_fmac_f32_e32 v17, v16, v10
	v_add_f32_e32 v12, 1.0, v12
	v_rcp_f32_e32 v12, v12
	v_add_f32_e32 v14, 1.0, v14
	v_rcp_f32_e32 v84, v14
	v_mov_b32_e32 v79, v17
	v_mul_f32_e32 v12, v109, v12
	v_exp_f32_e32 v85, v12
	v_mul_f32_e32 v10, v8, v87
	v_fma_f32 v12, -v85, v85, 1.0
	v_max_f32_e32 v12, 0, v12
	v_cmp_gt_f32_e32 vcc, s79, v12
	v_mul_f32_e32 v14, 0x4f800000, v12
	v_pk_mul_f32 v[78:79], v[78:79], v[84:85]
	v_cndmask_b32_e32 v12, v12, v14, vcc
	v_sqrt_f32_e32 v14, v12
	s_nop 0
	v_add_u32_e32 v16, -1, v14
	v_fma_f32 v67, -v16, v14, v12
	v_cmp_ge_f32_e64 s[16:17], 0, v67
	v_add_u32_e32 v67, 1, v14
	s_nop 0
	v_cndmask_b32_e64 v16, v14, v16, s[16:17]
	v_fma_f32 v14, -v67, v14, v12
	v_cmp_lt_f32_e64 s[16:17], 0, v14
	s_nop 1
	v_cndmask_b32_e64 v14, v16, v67, s[16:17]
	v_mul_f32_e32 v16, 0x37800000, v14
	v_cndmask_b32_e32 v14, v14, v16, vcc
	v_cmp_class_f32_e32 vcc, v12, v217
	s_nop 1
	v_cndmask_b32_e32 v12, v14, v12, vcc
	v_fmac_f32_e32 v79, v78, v12
	v_mul_f32_e32 v12, v10, v85
	ds_read2st64_b32 v[84:85], v205 offset0:68 offset1:70
	v_mov_b32_e32 v83, v79
	s_waitcnt lgkmcnt(0)
	v_add_f32_e32 v14, v107, v84
	v_mul_f32_e32 v14, 0xbfb8aa3b, v14
	v_exp_f32_e32 v14, v14
	v_add_f32_e32 v16, v108, v85
	v_mul_f32_e32 v16, 0xbfb8aa3b, v16
	v_exp_f32_e32 v16, v16
	v_add_f32_e32 v14, 1.0, v14
	v_rcp_f32_e32 v14, v14
	v_add_f32_e32 v16, 1.0, v16
	v_rcp_f32_e32 v84, v16
	v_mul_f32_e32 v14, v109, v14
	v_exp_f32_e32 v85, v14
	s_nop 0
	v_fma_f32 v14, -v85, v85, 1.0
	v_max_f32_e32 v14, 0, v14
	v_cmp_gt_f32_e32 vcc, s79, v14
	v_mul_f32_e32 v16, 0x4f800000, v14
	v_pk_mul_f32 v[82:83], v[82:83], v[84:85]
	v_cndmask_b32_e32 v14, v14, v16, vcc
	v_sqrt_f32_e32 v16, v14
	s_nop 0
	v_add_u32_e32 v67, -1, v16
	v_fma_f32 v69, -v67, v16, v14
	v_cmp_ge_f32_e64 s[16:17], 0, v69
	v_add_u32_e32 v69, 1, v16
	s_nop 0
	v_cndmask_b32_e64 v67, v16, v67, s[16:17]
	v_fma_f32 v16, -v69, v16, v14
	v_cmp_lt_f32_e64 s[16:17], 0, v16
	s_nop 1
	v_cndmask_b32_e64 v16, v67, v69, s[16:17]
	v_mul_f32_e32 v67, 0x37800000, v16
	v_cndmask_b32_e32 v16, v16, v67, vcc
	v_cmp_class_f32_e32 vcc, v14, v217
	s_nop 1
	v_cndmask_b32_e32 v14, v16, v14, vcc
	v_fmac_f32_e32 v83, v82, v14
	v_mul_f32_e32 v14, v12, v85
	ds_read2st64_b32 v[84:85], v206 offset0:68 offset1:70
	v_mov_b32_e32 v81, v83
	s_waitcnt lgkmcnt(0)
	v_add_f32_e32 v16, v107, v84
	v_mul_f32_e32 v16, 0xbfb8aa3b, v16
	v_exp_f32_e32 v16, v16
	v_add_f32_e32 v67, v108, v85
	v_mul_f32_e32 v67, 0xbfb8aa3b, v67
	v_exp_f32_e32 v67, v67
	v_add_f32_e32 v16, 1.0, v16
	v_rcp_f32_e32 v16, v16
	v_add_f32_e32 v67, 1.0, v67
	v_rcp_f32_e32 v84, v67
	v_mul_f32_e32 v16, v109, v16
	v_exp_f32_e32 v85, v16
	s_nop 0
	v_fma_f32 v16, -v85, v85, 1.0
	v_max_f32_e32 v16, 0, v16
	v_cmp_gt_f32_e32 vcc, s79, v16
	v_mul_f32_e32 v67, 0x4f800000, v16
	v_pk_mul_f32 v[80:81], v[80:81], v[84:85]
	v_cndmask_b32_e32 v16, v16, v67, vcc
	v_sqrt_f32_e32 v67, v16
	s_nop 0
	v_add_u32_e32 v69, -1, v67
	v_fma_f32 v71, -v69, v67, v16
	v_cmp_ge_f32_e64 s[16:17], 0, v71
	v_add_u32_e32 v71, 1, v67
	s_nop 0
	v_cndmask_b32_e64 v69, v67, v69, s[16:17]
	v_fma_f32 v67, -v71, v67, v16
	v_cmp_lt_f32_e64 s[16:17], 0, v67
	s_nop 1
	v_cndmask_b32_e64 v67, v69, v71, s[16:17]
	v_mul_f32_e32 v69, 0x37800000, v67
	v_cndmask_b32_e32 v67, v67, v69, vcc
	v_cmp_class_f32_e32 vcc, v16, v217
	s_nop 1
	v_cndmask_b32_e32 v16, v67, v16, vcc
	v_fmac_f32_e32 v81, v80, v16
	v_mul_f32_e32 v16, v14, v85
	ds_read2st64_b32 v[84:85], v207 offset0:68 offset1:70
	v_mov_b32_e32 v77, v81
	s_waitcnt lgkmcnt(0)
	v_add_f32_e32 v67, v107, v84
	v_mul_f32_e32 v67, 0xbfb8aa3b, v67
	v_exp_f32_e32 v67, v67
	v_add_f32_e32 v69, v108, v85
	v_mul_f32_e32 v69, 0xbfb8aa3b, v69
	v_exp_f32_e32 v69, v69
	v_add_f32_e32 v67, 1.0, v67
	v_rcp_f32_e32 v67, v67
	v_add_f32_e32 v69, 1.0, v69
	v_rcp_f32_e32 v84, v69
	v_mul_f32_e32 v67, v109, v67
	v_exp_f32_e32 v85, v67
	s_nop 0
	v_fma_f32 v67, -v85, v85, 1.0
	v_max_f32_e32 v67, 0, v67
	v_cmp_gt_f32_e32 vcc, s79, v67
	v_mul_f32_e32 v69, 0x4f800000, v67
	v_pk_mul_f32 v[76:77], v[76:77], v[84:85]
	v_cndmask_b32_e32 v67, v67, v69, vcc
	v_sqrt_f32_e32 v69, v67
	s_nop 0
	v_add_u32_e32 v71, -1, v69
	v_fma_f32 v73, -v71, v69, v67
	v_cmp_ge_f32_e64 s[16:17], 0, v73
	v_add_u32_e32 v73, 1, v69
	s_nop 0
	v_cndmask_b32_e64 v71, v69, v71, s[16:17]
	v_fma_f32 v69, -v73, v69, v67
	v_cmp_lt_f32_e64 s[16:17], 0, v69
	s_nop 1
	v_cndmask_b32_e64 v69, v71, v73, s[16:17]
	v_mul_f32_e32 v71, 0x37800000, v69
	v_cndmask_b32_e32 v69, v69, v71, vcc
	v_cmp_class_f32_e32 vcc, v67, v217
	s_nop 1
	v_cndmask_b32_e32 v67, v69, v67, vcc
	v_fmac_f32_e32 v77, v76, v67
	v_mul_f32_e32 v76, v16, v85
	ds_read2st64_b32 v[84:85], v208 offset0:68 offset1:70
	v_mov_b32_e32 v75, v77
	s_waitcnt lgkmcnt(0)
	v_add_f32_e32 v67, v107, v84
	v_mul_f32_e32 v67, 0xbfb8aa3b, v67
	v_exp_f32_e32 v67, v67
	v_add_f32_e32 v69, v108, v85
	v_mul_f32_e32 v69, 0xbfb8aa3b, v69
	v_exp_f32_e32 v69, v69
	v_add_f32_e32 v67, 1.0, v67
	v_rcp_f32_e32 v67, v67
	v_add_f32_e32 v69, 1.0, v69
	v_rcp_f32_e32 v84, v69
	v_mul_f32_e32 v67, v109, v67
	v_exp_f32_e32 v85, v67
	s_nop 0
	v_fma_f32 v67, -v85, v85, 1.0
	v_max_f32_e32 v67, 0, v67
	v_cmp_gt_f32_e32 vcc, s79, v67
	v_mul_f32_e32 v69, 0x4f800000, v67
	v_pk_mul_f32 v[74:75], v[74:75], v[84:85]
	v_cndmask_b32_e32 v67, v67, v69, vcc
	v_sqrt_f32_e32 v69, v67
	s_nop 0
	v_add_u32_e32 v71, -1, v69
	v_fma_f32 v73, -v71, v69, v67
	v_cmp_ge_f32_e64 s[16:17], 0, v73
	v_add_u32_e32 v73, 1, v69
	s_nop 0
	v_cndmask_b32_e64 v71, v69, v71, s[16:17]
	v_fma_f32 v69, -v73, v69, v67
	v_cmp_lt_f32_e64 s[16:17], 0, v69
	s_nop 1
	v_cndmask_b32_e64 v69, v71, v73, s[16:17]
	v_mul_f32_e32 v71, 0x37800000, v69
	v_cndmask_b32_e32 v69, v69, v71, vcc
	v_cmp_class_f32_e32 vcc, v67, v217
	s_nop 1
	v_cndmask_b32_e32 v67, v69, v67, vcc
	v_fmac_f32_e32 v75, v74, v67
	v_mul_f32_e32 v74, v76, v85
	ds_read2st64_b32 v[84:85], v209 offset0:68 offset1:70
	s_waitcnt lgkmcnt(0)
	v_add_f32_e32 v67, v107, v84
	v_mul_f32_e32 v67, 0xbfb8aa3b, v67
	v_exp_f32_e32 v67, v67
	v_add_f32_e32 v69, v108, v85
	v_mul_f32_e32 v69, 0xbfb8aa3b, v69
	v_exp_f32_e32 v69, v69
	v_add_f32_e32 v67, 1.0, v67
	v_rcp_f32_e32 v67, v67
	v_add_f32_e32 v69, 1.0, v69
	v_rcp_f32_e32 v84, v69
	v_mul_f32_e32 v67, v109, v67
	v_exp_f32_e32 v85, v67
	s_nop 0
	v_fma_f32 v67, -v85, v85, 1.0
	v_max_f32_e32 v67, 0, v67
	v_cmp_gt_f32_e32 vcc, s79, v67
	v_mul_f32_e32 v69, 0x4f800000, v67
	s_nop 0
	v_cndmask_b32_e32 v67, v67, v69, vcc
	v_sqrt_f32_e32 v69, v67
	s_nop 0
	v_add_u32_e32 v71, -1, v69
	v_fma_f32 v73, -v71, v69, v67
	v_cmp_ge_f32_e64 s[16:17], 0, v73
	v_add_u32_e32 v73, 1, v69
	s_nop 0
	v_cndmask_b32_e64 v71, v69, v71, s[16:17]
	v_fma_f32 v69, -v73, v69, v67
	v_cmp_lt_f32_e64 s[16:17], 0, v69
	s_nop 1
	v_cndmask_b32_e64 v69, v71, v73, s[16:17]
	v_mul_f32_e32 v71, 0x37800000, v69
	v_cndmask_b32_e32 v69, v69, v71, vcc
	v_cmp_class_f32_e32 vcc, v67, v217
	v_mov_b32_e32 v73, v75
	v_pk_mul_f32 v[72:73], v[72:73], v[84:85]
	v_cndmask_b32_e32 v67, v69, v67, vcc
	v_fmac_f32_e32 v73, v72, v67
	v_mul_f32_e32 v72, v74, v85
	ds_read2st64_b32 v[84:85], v210 offset0:68 offset1:70
	s_waitcnt lgkmcnt(0)
	v_add_f32_e32 v67, v107, v84
	v_mul_f32_e32 v67, 0xbfb8aa3b, v67
	v_exp_f32_e32 v67, v67
	v_add_f32_e32 v69, v108, v85
	v_mul_f32_e32 v69, 0xbfb8aa3b, v69
	v_exp_f32_e32 v69, v69
	v_add_f32_e32 v67, 1.0, v67
	v_rcp_f32_e32 v67, v67
	v_add_f32_e32 v69, 1.0, v69
	v_rcp_f32_e32 v84, v69
	v_mul_f32_e32 v67, v109, v67
	v_exp_f32_e32 v85, v67
	s_nop 0
	v_fma_f32 v67, -v85, v85, 1.0
	v_max_f32_e32 v67, 0, v67
	v_cmp_gt_f32_e32 vcc, s79, v67
	v_mul_f32_e32 v69, 0x4f800000, v67
	s_nop 0
	v_cndmask_b32_e32 v67, v67, v69, vcc
	v_sqrt_f32_e32 v69, v67
	s_nop 0
	v_add_u32_e32 v71, -1, v69
	v_fma_f32 v78, -v71, v69, v67
	v_cmp_ge_f32_e64 s[16:17], 0, v78
	v_add_u32_e32 v78, 1, v69
	s_nop 0
	v_cndmask_b32_e64 v71, v69, v71, s[16:17]
	v_fma_f32 v69, -v78, v69, v67
	v_cmp_lt_f32_e64 s[16:17], 0, v69
	s_nop 1
	v_cndmask_b32_e64 v69, v71, v78, s[16:17]
	v_mul_f32_e32 v71, 0x37800000, v69
	v_cndmask_b32_e32 v69, v69, v71, vcc
	v_cmp_class_f32_e32 vcc, v67, v217
	v_mov_b32_e32 v71, v73
	v_pk_mul_f32 v[70:71], v[70:71], v[84:85]
	v_cndmask_b32_e32 v67, v69, v67, vcc
	v_fmac_f32_e32 v71, v70, v67
	v_mul_f32_e32 v70, v72, v85
	ds_read2st64_b32 v[84:85], v211 offset0:68 offset1:70
	s_waitcnt lgkmcnt(0)
	v_add_f32_e32 v67, v107, v84
	v_mul_f32_e32 v67, 0xbfb8aa3b, v67
	v_exp_f32_e32 v67, v67
	v_add_f32_e32 v69, v108, v85
	v_mul_f32_e32 v69, 0xbfb8aa3b, v69
	v_exp_f32_e32 v69, v69
	v_add_f32_e32 v67, 1.0, v67
	v_rcp_f32_e32 v67, v67
	v_add_f32_e32 v69, 1.0, v69
	v_rcp_f32_e32 v84, v69
	v_mul_f32_e32 v67, v109, v67
	v_exp_f32_e32 v85, v67
	s_nop 0
	v_fma_f32 v67, -v85, v85, 1.0
	v_max_f32_e32 v67, 0, v67
	v_cmp_gt_f32_e32 vcc, s79, v67
	v_mul_f32_e32 v69, 0x4f800000, v67
	s_nop 0
	v_cndmask_b32_e32 v67, v67, v69, vcc
	v_sqrt_f32_e32 v69, v67
	s_nop 0
	v_add_u32_e32 v78, -1, v69
	v_fma_f32 v80, -v78, v69, v67
	v_cmp_ge_f32_e64 s[16:17], 0, v80
	v_add_u32_e32 v80, 1, v69
	s_nop 0
	v_cndmask_b32_e64 v78, v69, v78, s[16:17]
	v_fma_f32 v69, -v80, v69, v67
	v_cmp_lt_f32_e64 s[16:17], 0, v69
	s_nop 1
	v_cndmask_b32_e64 v69, v78, v80, s[16:17]
	v_mul_f32_e32 v78, 0x37800000, v69
	v_cndmask_b32_e32 v69, v69, v78, vcc
	v_cmp_class_f32_e32 vcc, v67, v217
	s_nop 1
	v_cndmask_b32_e32 v67, v69, v67, vcc
	v_mov_b32_e32 v69, v71
	v_pk_mul_f32 v[68:69], v[68:69], v[84:85]
	s_nop 0
	v_fmac_f32_e32 v69, v68, v67
	v_mul_f32_e32 v68, v70, v85
	ds_read2st64_b32 v[84:85], v212 offset0:68 offset1:70
	s_waitcnt lgkmcnt(0)
	v_add_f32_e32 v67, v107, v84
	v_mul_f32_e32 v67, 0xbfb8aa3b, v67
	v_exp_f32_e32 v67, v67
	v_add_f32_e32 v78, v108, v85
	v_mul_f32_e32 v78, 0xbfb8aa3b, v78
	v_exp_f32_e32 v78, v78
	v_add_f32_e32 v67, 1.0, v67
	v_rcp_f32_e32 v67, v67
	v_add_f32_e32 v78, 1.0, v78
	v_rcp_f32_e32 v84, v78
	v_mul_f32_e32 v67, v109, v67
	v_exp_f32_e32 v85, v67
	s_nop 0
	v_fma_f32 v67, -v85, v85, 1.0
	v_max_f32_e32 v67, 0, v67
	v_cmp_gt_f32_e32 vcc, s79, v67
	v_mul_f32_e32 v78, 0x4f800000, v67
	s_nop 0
	v_cndmask_b32_e32 v67, v67, v78, vcc
	v_sqrt_f32_e32 v78, v67
	s_nop 0
	v_add_u32_e32 v80, -1, v78
	v_fma_f32 v82, -v80, v78, v67
	v_cmp_ge_f32_e64 s[16:17], 0, v82
	v_add_u32_e32 v82, 1, v78
	s_nop 0
	v_cndmask_b32_e64 v80, v78, v80, s[16:17]
	v_fma_f32 v78, -v82, v78, v67
	v_cmp_lt_f32_e64 s[16:17], 0, v78
	s_nop 1
	v_cndmask_b32_e64 v78, v80, v82, s[16:17]
	v_mul_f32_e32 v80, 0x37800000, v78
	v_cndmask_b32_e32 v78, v78, v80, vcc
	v_cmp_class_f32_e32 vcc, v67, v217
	s_nop 1
	v_cndmask_b32_e32 v78, v78, v67, vcc
	v_mov_b32_e32 v67, v69
	v_pk_mul_f32 v[66:67], v[66:67], v[84:85]
	s_nop 0
	v_fmac_f32_e32 v67, v66, v78
	v_mul_f32_e32 v66, v68, v85
	v_lshl_add_u32 v78, s1, 2, v194
	ds_write_b64 v193, v[66:67]
	s_waitcnt lgkmcnt(0)
	s_waitcnt vmcnt(0)
	s_barrier
	ds_read_b32 v78, v78
	s_and_saveexec_b64 s[16:17], s[8:9]
	s_cbranch_execnz .LBB0_1328
	s_or_b64 exec, exec, s[16:17]
	s_and_saveexec_b64 s[16:17], s[12:13]
	s_cbranch_execnz .LBB0_1329

.LBB0_1322:
	s_or_b64 exec, exec, s[16:17]
	s_waitcnt lgkmcnt(0)
	v_fma_f32 v80, v66, v78, v67
	s_and_saveexec_b64 s[16:17], s[10:11]
	s_xor_b64 s[16:17], exec, s[16:17]
	v_fmac_f32_e32 v67, v66, v78
	s_andn2_saveexec_b64 s[16:17], s[16:17]
	s_cbranch_execz .LBB0_1313
	v_bitop3_b32 v66, s1, v226, v186 bitop3:0x36
	v_lshl_add_u32 v66, v66, 2, 0
	v_add_u32_e32 v66, 0x15800, v66
	v_mov_b32_e32 v67, v80
	ds_write_b32 v66, v80
	s_branch .LBB0_1313
.LBB0_1328:
	ds_read_b64 v[84:85], v195
	s_waitcnt lgkmcnt(0)
	v_fmac_f32_e32 v85, v78, v84
	v_mov_b32_e32 v78, v85
	s_or_b64 exec, exec, s[16:17]
	s_and_saveexec_b64 s[16:17], s[12:13]
	s_cbranch_execz .LBB0_1320

	.amdhsa_kernel _Z8mega_fwd6Params
		.amdhsa_group_segment_fixed_size 0
		.amdhsa_private_segment_fixed_size 0
		.amdhsa_kernarg_size 464
		.amdhsa_user_sgpr_count 2
		.amdhsa_user_sgpr_dispatch_ptr 0
		.amdhsa_user_sgpr_queue_ptr 0
		.amdhsa_user_sgpr_kernarg_segment_ptr 1
		.amdhsa_user_sgpr_dispatch_id 0
		.amdhsa_user_sgpr_kernarg_preload_length 0
		.amdhsa_user_sgpr_kernarg_preload_offset 0
		.amdhsa_user_sgpr_private_segment_size 0
		.amdhsa_uses_dynamic_stack 0
		.amdhsa_enable_private_segment 0
		.amdhsa_system_sgpr_workgroup_id_x 1
		.amdhsa_system_sgpr_workgroup_id_y 0
		.amdhsa_system_sgpr_workgroup_id_z 0
		.amdhsa_system_sgpr_workgroup_info 0
		.amdhsa_system_vgpr_workitem_id 2
		.amdhsa_next_free_vgpr 253
		.amdhsa_next_free_sgpr 102
		.amdhsa_accum_offset 256
		.amdhsa_reserve_vcc 1
		.amdhsa_float_round_mode_32 0
		.amdhsa_float_round_mode_16_64 0
		.amdhsa_float_denorm_mode_32 3
		.amdhsa_float_denorm_mode_16_64 3
		.amdhsa_dx10_clamp 1
		.amdhsa_ieee_mode 1
		.amdhsa_fp16_overflow 0
		.amdhsa_tg_split 0
		.amdhsa_exception_fp_ieee_invalid_op 0
		.amdhsa_exception_fp_denorm_src 0
		.amdhsa_exception_fp_ieee_div_zero 0
		.amdhsa_exception_fp_ieee_overflow 0
		.amdhsa_exception_fp_ieee_underflow 0
		.amdhsa_exception_fp_ieee_inexact 0
		.amdhsa_exception_int_div_zero 0
	.end_amdhsa_kernel

amdhsa.kernels:
  - .agpr_count:     0
    .args:
      - .offset:         0
        .size:           208
        .value_kind:     by_value
      - .offset:         208
        .size:           4
        .value_kind:     hidden_block_count_x
      - .offset:         212
        .size:           4
        .value_kind:     hidden_block_count_y
      - .offset:         216
        .size:           4
        .value_kind:     hidden_block_count_z
      - .offset:         220
        .size:           2
        .value_kind:     hidden_group_size_x
      - .offset:         222
        .size:           2
        .value_kind:     hidden_group_size_y
      - .offset:         224
        .size:           2
        .value_kind:     hidden_group_size_z
      - .offset:         226
        .size:           2
        .value_kind:     hidden_remainder_x
      - .offset:         228
        .size:           2
        .value_kind:     hidden_remainder_y
      - .offset:         230
        .size:           2
        .value_kind:     hidden_remainder_z
      - .offset:         248
        .size:           8
        .value_kind:     hidden_global_offset_x
      - .offset:         256
        .size:           8
        .value_kind:     hidden_global_offset_y
      - .offset:         264
        .size:           8
        .value_kind:     hidden_global_offset_z
      - .offset:         272
        .size:           2
        .value_kind:     hidden_grid_dims
      - .offset:         296
        .size:           8
        .value_kind:     hidden_multigrid_sync_arg
      - .offset:         328
        .size:           4
        .value_kind:     hidden_dynamic_lds_size
    .group_segment_fixed_size: 0
    .kernarg_segment_align: 8
    .kernarg_segment_size: 464
    .language:       OpenCL C
    .language_version:
      - 2
      - 0
    .max_flat_workgroup_size: 512
    .name:           _Z8mega_fwd6Params
    .private_segment_fixed_size: 0
    .sgpr_count:     108
    .sgpr_spill_count: 47
    .symbol:         _Z8mega_fwd6Params.kd
    .uniform_work_group_size: 1
    .uses_dynamic_stack: false
    .vgpr_count:     253
    .vgpr_spill_count: 0
    .wavefront_size: 64
